# q-projection rotary epilogue: lane^8 partner through DPP row_ror:8 instead of 64 ds_bpermute LDS round trips
# baseline (speedup 1.0000x reference)
; #define G_LOAD(RA, RB, kk) { const int ka_ = amode ? (((kk) >> 6) * 96) : (kk); \
;     _Pragma("unroll") for (int i = 0; i < 4; ++i) RA[i] = *(const u32x4*)(A + (size_t)(lr + 32 * i) * lda + ka_ + lk); \
;     _Pragma("unroll") for (int i = 0; i < NB2; ++i) RB[i] = *(const u32x4*)(Bt + (size_t)(lr + 32 * i) * ldb + (kk) + lk); }
; template <int NT>
; DI void gemm_main(f32x16 (&acc)[2][NT], const u16* __restrict__ A, int lda, int amode, const u16* __restrict__ Bt,
;                   int ldb, int K, char* smem) {
;     ...
;   const int nk = K >> 6;
;   G_LOAD(ra0, rb0, 0)
;   __syncthreads();
; #pragma unroll
;   for (int i = 0; i < 4; ++i) G_STORE_A(ra0, 0, i)
; #pragma unroll
;   for (int i = 0; i < NB2; ++i) G_STORE_B(rb0, 0, i)
;   G_LOAD(ra0, rb0, 64)
;   __syncthreads();
;   for (int kt = 0; kt < nk; kt += 2) {
;     const bool more2 = kt + 2 < nk;
;     if (more2) G_LOAD(ra1, rb1, (kt + 2) * 64)
;     G_STEP(ra0, rb0, 0, 0, true) G_STEP(ra0, rb0, 0, 1, true) G_STEP(ra0, rb0, 0, 2, true) G_STEP(ra0, rb0, 0, 3, true)
.LBB0_735:
	s_or_b64 exec, exec, s[8:9]
	s_mul_i32 s5, s5, -6
	s_lshl_b32 s2, s3, 7
	s_add_i32 s4, s5, s4
	s_mul_i32 s8, s3, 0x2a000
	s_mul_hi_i32 s5, s3, 0x2a000
	s_add_u32 s8, s6, s8
	s_addc_u32 s5, s7, s5
	s_add_u32 s8, s8, 0x2200000
	s_addc_u32 s9, s5, 0
	s_mul_i32 s10, s4, 0x18000
	s_mul_hi_i32 s5, s4, 0x18000
	s_add_u32 s10, s6, s10
	s_addc_u32 s5, s7, s5
	v_mov_b32_e32 v52, v0
	s_add_u32 s10, s10, 0xddd0000
	s_addc_u32 s11, s5, 0
	s_waitcnt lgkmcnt(0)
	v_lshlrev_b32_e32 v2, 4, v52
	v_ashrrev_i32_e32 v46, 3, v52
	v_and_b32_e32 v198, 0x70, v2
	v_lshl_add_u64 v[10:11], s[8:9], 0, v[198:199]
	s_movk_i32 s14, 0x540
	v_add_u32_e32 v53, 64, v46
	v_lshl_add_u64 v[26:27], s[10:11], 0, v[198:199]
	s_movk_i32 s5, 0x300
	v_mad_i64_i32 v[70:71], s[12:13], v46, s14, v[10:11]
	v_add_u32_e32 v50, 32, v46
	v_mad_i64_i32 v[74:75], s[12:13], v53, s14, v[10:11]
	v_add_u32_e32 v54, 0x60, v46
	v_mad_i64_i32 v[78:79], s[12:13], v46, s5, v[26:27]
	v_mad_i64_i32 v[82:83], s[12:13], v53, s5, v[26:27]
	v_mad_i64_i32 v[72:73], s[12:13], v50, s14, v[10:11]
	global_load_dwordx4 v[2:5], v[70:71], off
	global_load_dwordx4 v[6:9], v[72:73], off
	v_mad_i64_i32 v[76:77], s[12:13], v54, s14, v[10:11]
	global_load_dwordx4 v[10:13], v[74:75], off
	global_load_dwordx4 v[14:17], v[76:77], off
	v_mad_i64_i32 v[80:81], s[12:13], v50, s5, v[26:27]
	global_load_dwordx4 v[18:21], v[78:79], off
	global_load_dwordx4 v[22:25], v[80:81], off
	v_mad_i64_i32 v[84:85], s[12:13], v54, s5, v[26:27]
	global_load_dwordx4 v[26:29], v[82:83], off
	global_load_dwordx4 v[30:33], v[84:85], off
	v_mov_b64_e32 v[42:43], s[8:9]
	v_mad_i64_i32 v[34:35], s[8:9], v46, s14, v[42:43]
	v_mov_b64_e32 v[44:45], s[10:11]
	v_lshl_add_u64 v[34:35], v[34:35], 0, v[198:199]
	v_mad_i64_i32 v[38:39], s[8:9], v46, s5, v[44:45]
	s_barrier
	global_load_dwordx4 v[34:37], v[34:35], off offset:128
	v_lshl_add_u64 v[38:39], v[38:39], 0, v[198:199]
	global_load_dwordx4 v[38:41], v[38:39], off offset:128
	v_mad_u64_u32 v[68:69], s[8:9], v46, s60, v[198:199]
	v_mad_i64_i32 v[46:47], s[8:9], v50, s14, v[42:43]
	v_lshl_add_u64 v[46:47], v[46:47], 0, v[198:199]
	v_mad_i64_i32 v[50:51], s[8:9], v50, s5, v[44:45]
	global_load_dwordx4 v[90:93], v[46:47], off offset:128
	v_lshl_add_u64 v[46:47], v[50:51], 0, v[198:199]
	global_load_dwordx4 v[94:97], v[46:47], off offset:128
	v_mad_i64_i32 v[48:49], s[8:9], v53, s14, v[42:43]
	v_mad_i64_i32 v[42:43], s[8:9], v54, s14, v[42:43]
	v_lshl_add_u64 v[46:47], v[48:49], 0, v[198:199]
	v_lshl_add_u64 v[42:43], v[42:43], 0, v[198:199]
	v_mad_i64_i32 v[48:49], s[8:9], v53, s5, v[44:45]
	global_load_dwordx4 v[98:101], v[46:47], off offset:128
	global_load_dwordx4 v[102:105], v[42:43], off offset:128
	v_lshl_add_u64 v[42:43], v[48:49], 0, v[198:199]
	v_and_b32_e32 v55, 31, v52
	v_add_u32_e32 v69, 0xd800, v68
	s_cmpk_lt_i32 s3, 0x80
	s_cselect_b64 s[14:15], -1, 0
	s_lshl_b32 s3, s4, 7
	s_movk_i32 s48, 0x300
	s_waitcnt vmcnt(13)
	ds_write_b128 v68, v[2:5]
	s_waitcnt vmcnt(12)
	ds_write_b128 v68, v[6:9] offset:4608
	s_waitcnt vmcnt(11)
	ds_write_b128 v68, v[10:13] offset:9216
	s_waitcnt vmcnt(10)
	ds_write_b128 v68, v[14:17] offset:13824
	s_waitcnt vmcnt(9)
	ds_write_b128 v68, v[18:21] offset:18432
	s_waitcnt vmcnt(8)
	ds_write_b128 v68, v[22:25] offset:23040
	s_waitcnt vmcnt(7)
	ds_write_b128 v68, v[26:29] offset:27648
	s_waitcnt vmcnt(6)
	ds_write_b128 v68, v[30:33] offset:32256
	v_mad_i64_i32 v[2:3], s[8:9], v54, s5, v[44:45]
	v_lshl_add_u64 v[2:3], v[2:3], 0, v[198:199]
	global_load_dwordx4 v[106:109], v[42:43], off offset:128
	global_load_dwordx4 v[110:113], v[2:3], off offset:128
	s_waitcnt lgkmcnt(0)
	s_barrier
	global_load_dwordx4 v[114:117], v[70:71], off offset:256
	global_load_dwordx4 v[118:121], v[72:73], off offset:256
	global_load_dwordx4 v[122:125], v[74:75], off offset:256
	global_load_dwordx4 v[126:129], v[76:77], off offset:256
	global_load_dwordx4 v[130:133], v[78:79], off offset:256
	global_load_dwordx4 v[134:137], v[80:81], off offset:256
	global_load_dwordx4 v[138:141], v[82:83], off offset:256
	global_load_dwordx4 v[142:145], v[84:85], off offset:256
	v_lshrrev_b32_e32 v2, 1, v52
	v_and_or_b32 v3, v2, s31, v55
	v_and_b32_e32 v6, 16, v2
	s_waitcnt vmcnt(15)
	ds_write_b128 v68, v[34:37] offset:36864
	s_waitcnt vmcnt(14)
	ds_write_b128 v68, v[38:41] offset:55296
	v_mad_u64_u32 v[66:67], s[8:9], v3, s60, v[6:7]
	ds_read_b128 v[2:5], v66
	v_and_b32_e32 v7, 0x5f, v52
	v_mad_u32_u24 v67, v7, s60, v6
	ds_read_b128 v[6:9], v67 offset:18432
	ds_read_b128 v[10:13], v67 offset:23040
	s_waitcnt lgkmcnt(1)
	v_mfma_f32_32x32x16_bf16 v[50:65], v[2:5], v[6:9], 0
	s_waitcnt lgkmcnt(0)
	v_mfma_f32_32x32x16_bf16 v[34:49], v[2:5], v[10:13], 0
	ds_read_b128 v[2:5], v66 offset:4608
	s_waitcnt vmcnt(13)
	ds_write_b128 v68, v[90:93] offset:41472
	s_waitcnt vmcnt(12)
	ds_write_b128 v68, v[94:97] offset:59904
	ds_read_b128 v[90:93], v66 offset:32
	ds_read_b128 v[94:97], v67 offset:18464
	ds_read_b128 v[146:149], v67 offset:23072
	s_waitcnt lgkmcnt(1)
	v_mfma_f32_32x32x16_bf16 v[50:65], v[90:93], v[94:97], v[50:65]
	s_waitcnt lgkmcnt(0)
	v_mfma_f32_32x32x16_bf16 v[34:49], v[90:93], v[146:149], v[34:49]
	ds_read_b128 v[90:93], v66 offset:4640
	s_waitcnt vmcnt(11)
	ds_write_b128 v68, v[98:101] offset:46080
	s_waitcnt vmcnt(9)
	ds_write_b128 v68, v[106:109] offset:64512
	v_mfma_f32_32x32x16_bf16 v[18:33], v[2:5], v[6:9], 0
	v_mfma_f32_32x32x16_bf16 v[2:17], v[2:5], v[10:13], 0
	s_waitcnt lgkmcnt(2)
	v_mfma_f32_32x32x16_bf16 v[18:33], v[90:93], v[94:97], v[18:33]
	v_mfma_f32_32x32x16_bf16 v[2:17], v[90:93], v[146:149], v[2:17]
	ds_read_b128 v[90:93], v66 offset:64
	ds_read_b128 v[94:97], v67 offset:18496
	ds_read_b128 v[98:101], v67 offset:23104
	s_waitcnt lgkmcnt(1)
	v_mfma_f32_32x32x16_bf16 v[50:65], v[90:93], v[94:97], v[50:65]
	s_waitcnt lgkmcnt(0)
	v_mfma_f32_32x32x16_bf16 v[34:49], v[90:93], v[98:101], v[34:49]
	ds_read_b128 v[90:93], v66 offset:4672
	ds_write_b128 v68, v[102:105] offset:50688
	s_waitcnt vmcnt(8)
	ds_write_b128 v69, v[110:113] offset:13824
	s_waitcnt lgkmcnt(2)
	v_mfma_f32_32x32x16_bf16 v[18:33], v[90:93], v[94:97], v[18:33]
	v_mfma_f32_32x32x16_bf16 v[2:17], v[90:93], v[98:101], v[2:17]
	ds_read_b128 v[90:93], v66 offset:96
	ds_read_b128 v[94:97], v67 offset:18528
	ds_read_b128 v[98:101], v67 offset:23136
	s_waitcnt lgkmcnt(1)
	v_mfma_f32_32x32x16_bf16 v[50:65], v[90:93], v[94:97], v[50:65]
	s_waitcnt lgkmcnt(0)
	v_mfma_f32_32x32x16_bf16 v[34:49], v[90:93], v[98:101], v[34:49]
	ds_read_b128 v[90:93], v66 offset:4704
	s_waitcnt lgkmcnt(0)
	s_barrier
; #define G_LOAD(RA, RB, kk) { const int ka_ = amode ? (((kk) >> 6) * 96) : (kk); \
;     _Pragma("unroll") for (int i = 0; i < 4; ++i) RA[i] = *(const u32x4*)(A + (size_t)(lr + 32 * i) * lda + ka_ + lk); \
;     _Pragma("unroll") for (int i = 0; i < NB2; ++i) RB[i] = *(const u32x4*)(Bt + (size_t)(lr + 32 * i) * ldb + (kk) + lk); }
; template <int NT>
; DI void gemm_main(f32x16 (&acc)[2][NT], const u16* __restrict__ A, int lda, int amode, const u16* __restrict__ Bt,
;                   int ldb, int K, char* smem) {
;     ...
;   for (int kt = 0; kt < nk; kt += 2) {
;     const bool more2 = kt + 2 < nk;
;     if (more2) G_LOAD(ra1, rb1, (kt + 2) * 64)
;     G_STEP(ra0, rb0, 0, 0, true) G_STEP(ra0, rb0, 0, 1, true) G_STEP(ra0, rb0, 0, 2, true) G_STEP(ra0, rb0, 0, 3, true)
;     __syncthreads();
;     if (kt + 3 < nk) G_LOAD(ra0, rb0, (kt + 3) * 64)
;     G_STEP(ra1, rb1, 1, 0, more2) G_STEP(ra1, rb1, 1, 1, more2) G_STEP(ra1, rb1, 1, 2, more2) G_STEP(ra1, rb1, 1, 3, more2)
;     __syncthreads();
	v_mfma_f32_32x32x16_bf16 v[18:33], v[90:93], v[94:97], v[18:33]
	v_mfma_f32_32x32x16_bf16 v[2:17], v[90:93], v[98:101], v[2:17]
	global_load_dwordx4 v[90:93], v[70:71], off offset:384
	global_load_dwordx4 v[94:97], v[72:73], off offset:384
	global_load_dwordx4 v[98:101], v[74:75], off offset:384
	global_load_dwordx4 v[102:105], v[76:77], off offset:384
	global_load_dwordx4 v[106:109], v[78:79], off offset:384
	global_load_dwordx4 v[110:113], v[80:81], off offset:384
	global_load_dwordx4 v[146:149], v[82:83], off offset:384
	global_load_dwordx4 v[150:153], v[84:85], off offset:384
	s_waitcnt vmcnt(15)
	ds_write_b128 v68, v[114:117]
	s_waitcnt vmcnt(11)
	ds_write_b128 v68, v[130:133] offset:18432
	ds_read_b128 v[114:117], v66 offset:36864
	ds_read_b128 v[130:133], v67 offset:55296
	ds_read_b128 v[154:157], v67 offset:59904
	s_waitcnt lgkmcnt(1)
	v_mfma_f32_32x32x16_bf16 v[50:65], v[114:117], v[130:133], v[50:65]
	s_waitcnt lgkmcnt(0)
	v_mfma_f32_32x32x16_bf16 v[34:49], v[114:117], v[154:157], v[34:49]
	ds_read_b128 v[114:117], v66 offset:41472
	ds_write_b128 v68, v[118:121] offset:4608
	s_waitcnt vmcnt(10)
	ds_write_b128 v68, v[134:137] offset:23040
	s_waitcnt lgkmcnt(2)
	v_mfma_f32_32x32x16_bf16 v[18:33], v[114:117], v[130:133], v[18:33]
	v_mfma_f32_32x32x16_bf16 v[2:17], v[114:117], v[154:157], v[2:17]
	ds_read_b128 v[114:117], v66 offset:36896
	ds_read_b128 v[118:121], v67 offset:55328
	ds_read_b128 v[130:133], v67 offset:59936
	s_waitcnt lgkmcnt(1)
	v_mfma_f32_32x32x16_bf16 v[50:65], v[114:117], v[118:121], v[50:65]
	s_waitcnt lgkmcnt(0)
	v_mfma_f32_32x32x16_bf16 v[34:49], v[114:117], v[130:133], v[34:49]
	ds_read_b128 v[114:117], v66 offset:41504
	ds_write_b128 v68, v[122:125] offset:9216
	s_waitcnt vmcnt(9)
	ds_write_b128 v68, v[138:141] offset:27648
	s_waitcnt lgkmcnt(2)
	v_mfma_f32_32x32x16_bf16 v[18:33], v[114:117], v[118:121], v[18:33]
	v_mfma_f32_32x32x16_bf16 v[2:17], v[114:117], v[130:133], v[2:17]
	ds_read_b128 v[114:117], v66 offset:36928
	ds_read_b128 v[118:121], v67 offset:55360
	ds_read_b128 v[122:125], v67 offset:59968
	s_waitcnt lgkmcnt(1)
	v_mfma_f32_32x32x16_bf16 v[50:65], v[114:117], v[118:121], v[50:65]
	s_waitcnt lgkmcnt(0)
	v_mfma_f32_32x32x16_bf16 v[34:49], v[114:117], v[122:125], v[34:49]
	ds_read_b128 v[114:117], v66 offset:41536
	ds_write_b128 v68, v[126:129] offset:13824
	s_waitcnt vmcnt(8)
	ds_write_b128 v68, v[142:145] offset:32256
	s_waitcnt lgkmcnt(2)
	v_mfma_f32_32x32x16_bf16 v[18:33], v[114:117], v[118:121], v[18:33]
	v_mfma_f32_32x32x16_bf16 v[2:17], v[114:117], v[122:125], v[2:17]
	ds_read_b128 v[114:117], v66 offset:36960
	ds_read_b128 v[118:121], v67 offset:55392
	ds_read_b128 v[122:125], v67 offset:60000
	s_waitcnt lgkmcnt(1)
	v_mfma_f32_32x32x16_bf16 v[50:65], v[114:117], v[118:121], v[50:65]
	s_waitcnt lgkmcnt(0)
	v_mfma_f32_32x32x16_bf16 v[34:49], v[114:117], v[122:125], v[34:49]
	ds_read_b128 v[114:117], v66 offset:41568
	s_waitcnt lgkmcnt(0)
	s_barrier
	v_mfma_f32_32x32x16_bf16 v[18:33], v[114:117], v[118:121], v[18:33]
	v_mfma_f32_32x32x16_bf16 v[2:17], v[114:117], v[122:125], v[2:17]
	global_load_dwordx4 v[114:117], v[70:71], off offset:512
	global_load_dwordx4 v[118:121], v[72:73], off offset:512
	global_load_dwordx4 v[122:125], v[74:75], off offset:512
	global_load_dwordx4 v[126:129], v[76:77], off offset:512
	global_load_dwordx4 v[130:133], v[78:79], off offset:512
	global_load_dwordx4 v[134:137], v[80:81], off offset:512
	global_load_dwordx4 v[138:141], v[82:83], off offset:512
	global_load_dwordx4 v[142:145], v[84:85], off offset:512
	s_waitcnt vmcnt(15)
	ds_write_b128 v68, v[90:93] offset:36864
	s_waitcnt vmcnt(11)
	ds_write_b128 v68, v[106:109] offset:55296
	ds_read_b128 v[90:93], v66
	ds_read_b128 v[106:109], v67 offset:18432
	ds_read_b128 v[154:157], v67 offset:23040
	s_waitcnt lgkmcnt(1)
	v_mfma_f32_32x32x16_bf16 v[50:65], v[90:93], v[106:109], v[50:65]
	s_waitcnt lgkmcnt(0)
	v_mfma_f32_32x32x16_bf16 v[34:49], v[90:93], v[154:157], v[34:49]
	ds_read_b128 v[90:93], v66 offset:4608
	ds_write_b128 v68, v[94:97] offset:41472
	s_waitcnt vmcnt(10)
	ds_write_b128 v68, v[110:113] offset:59904
	s_waitcnt lgkmcnt(2)
	v_mfma_f32_32x32x16_bf16 v[18:33], v[90:93], v[106:109], v[18:33]
	v_mfma_f32_32x32x16_bf16 v[2:17], v[90:93], v[154:157], v[2:17]
	ds_read_b128 v[90:93], v66 offset:32
	ds_read_b128 v[94:97], v67 offset:18464
	ds_read_b128 v[106:109], v67 offset:23072
	s_waitcnt lgkmcnt(1)
	v_mfma_f32_32x32x16_bf16 v[50:65], v[90:93], v[94:97], v[50:65]
	s_waitcnt lgkmcnt(0)
	v_mfma_f32_32x32x16_bf16 v[34:49], v[90:93], v[106:109], v[34:49]
	ds_read_b128 v[90:93], v66 offset:4640
	ds_write_b128 v68, v[98:101] offset:46080
	s_waitcnt vmcnt(9)
	ds_write_b128 v68, v[146:149] offset:64512
	s_waitcnt lgkmcnt(2)
	v_mfma_f32_32x32x16_bf16 v[18:33], v[90:93], v[94:97], v[18:33]
	v_mfma_f32_32x32x16_bf16 v[2:17], v[90:93], v[106:109], v[2:17]
	ds_read_b128 v[90:93], v66 offset:64
	ds_read_b128 v[94:97], v67 offset:18496
	ds_read_b128 v[98:101], v67 offset:23104
	s_waitcnt lgkmcnt(1)
	v_mfma_f32_32x32x16_bf16 v[50:65], v[90:93], v[94:97], v[50:65]
	s_waitcnt lgkmcnt(0)
	v_mfma_f32_32x32x16_bf16 v[34:49], v[90:93], v[98:101], v[34:49]
	ds_read_b128 v[90:93], v66 offset:4672
	ds_write_b128 v68, v[102:105] offset:50688
	s_waitcnt vmcnt(8)
	ds_write_b128 v69, v[150:153] offset:13824
	s_waitcnt lgkmcnt(2)
	v_mfma_f32_32x32x16_bf16 v[18:33], v[90:93], v[94:97], v[18:33]
	v_mfma_f32_32x32x16_bf16 v[2:17], v[90:93], v[98:101], v[2:17]
	ds_read_b128 v[90:93], v66 offset:96
	ds_read_b128 v[94:97], v67 offset:18528
	ds_read_b128 v[98:101], v67 offset:23136
	s_waitcnt lgkmcnt(1)
	v_mfma_f32_32x32x16_bf16 v[50:65], v[90:93], v[94:97], v[50:65]
	s_waitcnt lgkmcnt(0)
	v_mfma_f32_32x32x16_bf16 v[34:49], v[90:93], v[98:101], v[34:49]
	ds_read_b128 v[90:93], v66 offset:4704
	s_waitcnt lgkmcnt(0)
	s_barrier
; #define G_LOAD(RA, RB, kk) { const int ka_ = amode ? (((kk) >> 6) * 96) : (kk); \
;     _Pragma("unroll") for (int i = 0; i < 4; ++i) RA[i] = *(const u32x4*)(A + (size_t)(lr + 32 * i) * lda + ka_ + lk); \
;     _Pragma("unroll") for (int i = 0; i < NB2; ++i) RB[i] = *(const u32x4*)(Bt + (size_t)(lr + 32 * i) * ldb + (kk) + lk); }
; template <int NT>
; DI void gemm_main(f32x16 (&acc)[2][NT], const u16* __restrict__ A, int lda, int amode, const u16* __restrict__ Bt,
;                   int ldb, int K, char* smem) {
;     ...
;   for (int kt = 0; kt < nk; kt += 2) {
;     const bool more2 = kt + 2 < nk;
;     if (more2) G_LOAD(ra1, rb1, (kt + 2) * 64)
;     G_STEP(ra0, rb0, 0, 0, true) G_STEP(ra0, rb0, 0, 1, true) G_STEP(ra0, rb0, 0, 2, true) G_STEP(ra0, rb0, 0, 3, true)
;     __syncthreads();
;     if (kt + 3 < nk) G_LOAD(ra0, rb0, (kt + 3) * 64)
;     G_STEP(ra1, rb1, 1, 0, more2) G_STEP(ra1, rb1, 1, 1, more2) G_STEP(ra1, rb1, 1, 2, more2) G_STEP(ra1, rb1, 1, 3, more2)
;     __syncthreads();
	v_mfma_f32_32x32x16_bf16 v[18:33], v[90:93], v[94:97], v[18:33]
	v_mfma_f32_32x32x16_bf16 v[2:17], v[90:93], v[98:101], v[2:17]
	global_load_dwordx4 v[90:93], v[70:71], off offset:640
	s_nop 0
	global_load_dwordx4 v[70:73], v[72:73], off offset:640
	s_nop 0
	global_load_dwordx4 v[94:97], v[74:75], off offset:640
	s_nop 0
	global_load_dwordx4 v[74:77], v[76:77], off offset:640
	s_nop 0
	global_load_dwordx4 v[98:101], v[78:79], off offset:640
	s_nop 0
	global_load_dwordx4 v[78:81], v[80:81], off offset:640
	s_nop 0
	global_load_dwordx4 v[102:105], v[82:83], off offset:640
	s_nop 0
	global_load_dwordx4 v[82:85], v[84:85], off offset:640
	s_waitcnt vmcnt(15)
	ds_write_b128 v68, v[114:117]
	s_waitcnt vmcnt(11)
	ds_write_b128 v68, v[130:133] offset:18432
	ds_read_b128 v[106:109], v66 offset:36864
	ds_read_b128 v[110:113], v67 offset:55296
	ds_read_b128 v[114:117], v67 offset:59904
	s_waitcnt lgkmcnt(1)
	v_mfma_f32_32x32x16_bf16 v[50:65], v[106:109], v[110:113], v[50:65]
	s_waitcnt lgkmcnt(0)
	v_mfma_f32_32x32x16_bf16 v[34:49], v[106:109], v[114:117], v[34:49]
	ds_read_b128 v[106:109], v66 offset:41472
	ds_write_b128 v68, v[118:121] offset:4608
	s_waitcnt vmcnt(10)
	ds_write_b128 v68, v[134:137] offset:23040
	s_waitcnt lgkmcnt(2)
	v_mfma_f32_32x32x16_bf16 v[18:33], v[106:109], v[110:113], v[18:33]
	v_mfma_f32_32x32x16_bf16 v[2:17], v[106:109], v[114:117], v[2:17]
	ds_read_b128 v[106:109], v66 offset:36896
	ds_read_b128 v[110:113], v67 offset:55328
	ds_read_b128 v[114:117], v67 offset:59936
	s_waitcnt lgkmcnt(1)
	v_mfma_f32_32x32x16_bf16 v[50:65], v[106:109], v[110:113], v[50:65]
	s_waitcnt lgkmcnt(0)
	v_mfma_f32_32x32x16_bf16 v[34:49], v[106:109], v[114:117], v[34:49]
	ds_read_b128 v[106:109], v66 offset:41504
	ds_write_b128 v68, v[122:125] offset:9216
	s_waitcnt vmcnt(9)
	ds_write_b128 v68, v[138:141] offset:27648
	s_waitcnt lgkmcnt(2)
	v_mfma_f32_32x32x16_bf16 v[18:33], v[106:109], v[110:113], v[18:33]
	v_mfma_f32_32x32x16_bf16 v[2:17], v[106:109], v[114:117], v[2:17]
	ds_read_b128 v[106:109], v66 offset:36928
	ds_read_b128 v[110:113], v67 offset:55360
	ds_read_b128 v[114:117], v67 offset:59968
	s_waitcnt lgkmcnt(1)
	v_mfma_f32_32x32x16_bf16 v[50:65], v[106:109], v[110:113], v[50:65]
	s_waitcnt lgkmcnt(0)
	v_mfma_f32_32x32x16_bf16 v[34:49], v[106:109], v[114:117], v[34:49]
	ds_read_b128 v[106:109], v66 offset:41536
	ds_write_b128 v68, v[126:129] offset:13824
	s_waitcnt vmcnt(8)
	ds_write_b128 v68, v[142:145] offset:32256
	s_waitcnt lgkmcnt(2)
	v_mfma_f32_32x32x16_bf16 v[18:33], v[106:109], v[110:113], v[18:33]
	v_mfma_f32_32x32x16_bf16 v[2:17], v[106:109], v[114:117], v[2:17]
	ds_read_b128 v[106:109], v66 offset:36960
	ds_read_b128 v[110:113], v67 offset:55392
	ds_read_b128 v[114:117], v67 offset:60000
	s_waitcnt lgkmcnt(1)
	v_mfma_f32_32x32x16_bf16 v[50:65], v[106:109], v[110:113], v[50:65]
	s_waitcnt lgkmcnt(0)
	v_mfma_f32_32x32x16_bf16 v[34:49], v[106:109], v[114:117], v[34:49]
	ds_read_b128 v[106:109], v66 offset:41568
	s_waitcnt lgkmcnt(0)
	s_barrier
	s_waitcnt vmcnt(7)
	ds_write_b128 v68, v[90:93] offset:36864
	s_waitcnt vmcnt(3)
	ds_write_b128 v68, v[98:101] offset:55296
	v_mfma_f32_32x32x16_bf16 v[18:33], v[106:109], v[110:113], v[18:33]
	ds_read_b128 v[90:93], v66
	ds_read_b128 v[98:101], v67 offset:18432
	v_mfma_f32_32x32x16_bf16 v[2:17], v[106:109], v[114:117], v[2:17]
	ds_read_b128 v[106:109], v67 offset:23040
	s_waitcnt lgkmcnt(1)
	v_mfma_f32_32x32x16_bf16 v[50:65], v[90:93], v[98:101], v[50:65]
	s_waitcnt lgkmcnt(0)
	v_mfma_f32_32x32x16_bf16 v[34:49], v[90:93], v[106:109], v[34:49]
	ds_read_b128 v[90:93], v66 offset:4608
	ds_write_b128 v68, v[70:73] offset:41472
	s_waitcnt vmcnt(2)
	ds_write_b128 v68, v[78:81] offset:59904
	ds_read_b128 v[70:73], v66 offset:32
	ds_read_b128 v[78:81], v67 offset:18464
	s_waitcnt lgkmcnt(4)
	v_mfma_f32_32x32x16_bf16 v[18:33], v[90:93], v[98:101], v[18:33]
	v_mfma_f32_32x32x16_bf16 v[2:17], v[90:93], v[106:109], v[2:17]
	ds_read_b128 v[90:93], v67 offset:23072
	s_waitcnt lgkmcnt(1)
	v_mfma_f32_32x32x16_bf16 v[50:65], v[70:73], v[78:81], v[50:65]
	s_waitcnt lgkmcnt(0)
	v_mfma_f32_32x32x16_bf16 v[34:49], v[70:73], v[90:93], v[34:49]
	ds_read_b128 v[70:73], v66 offset:4640
	ds_write_b128 v68, v[94:97] offset:46080
	s_waitcnt vmcnt(1)
	ds_write_b128 v68, v[102:105] offset:64512
	s_waitcnt lgkmcnt(2)
	v_mfma_f32_32x32x16_bf16 v[18:33], v[70:73], v[78:81], v[18:33]
	v_mfma_f32_32x32x16_bf16 v[2:17], v[70:73], v[90:93], v[2:17]
	ds_read_b128 v[70:73], v66 offset:64
	ds_read_b128 v[78:81], v67 offset:18496
	ds_read_b128 v[90:93], v67 offset:23104
	s_waitcnt lgkmcnt(1)
	v_mfma_f32_32x32x16_bf16 v[50:65], v[70:73], v[78:81], v[50:65]
	s_waitcnt lgkmcnt(0)
	v_mfma_f32_32x32x16_bf16 v[34:49], v[70:73], v[90:93], v[34:49]
	ds_read_b128 v[70:73], v66 offset:4672
	ds_write_b128 v68, v[74:77] offset:50688
	s_waitcnt vmcnt(0)
	ds_write_b128 v69, v[82:85] offset:13824
	s_waitcnt lgkmcnt(2)
	v_mfma_f32_32x32x16_bf16 v[18:33], v[70:73], v[78:81], v[18:33]
	v_mfma_f32_32x32x16_bf16 v[2:17], v[70:73], v[90:93], v[2:17]
	ds_read_b128 v[68:71], v66 offset:96
	ds_read_b128 v[72:75], v67 offset:18528
	ds_read_b128 v[76:79], v67 offset:23136
	s_waitcnt lgkmcnt(1)
	v_mfma_f32_32x32x16_bf16 v[50:65], v[68:71], v[72:75], v[50:65]
	s_waitcnt lgkmcnt(0)
	v_mfma_f32_32x32x16_bf16 v[34:49], v[68:71], v[76:79], v[34:49]
	ds_read_b128 v[68:71], v66 offset:4704
	s_waitcnt lgkmcnt(0)
	s_barrier
; DI int crow(int r, int hh) { return (r & 3) + 8 * (r >> 2) + 4 * hh; }
; #define G_LOAD(RA, RB, kk) { const int ka_ = amode ? (((kk) >> 6) * 96) : (kk); \
;     _Pragma("unroll") for (int i = 0; i < 4; ++i) RA[i] = *(const u32x4*)(A + (size_t)(lr + 32 * i) * lda + ka_ + lk); \
;     _Pragma("unroll") for (int i = 0; i < NB2; ++i) RB[i] = *(const u32x4*)(Bt + (size_t)(lr + 32 * i) * ldb + (kk) + lk); }
; template <int NT>
; DI void gemm_main(f32x16 (&acc)[2][NT], const u16* __restrict__ A, int lda, int amode, const u16* __restrict__ Bt,
;                   int ldb, int K, char* smem) {
;     ...
;   for (int kt = 0; kt < nk; kt += 2) {
;     const bool more2 = kt + 2 < nk;
;     if (more2) G_LOAD(ra1, rb1, (kt + 2) * 64)
;     G_STEP(ra0, rb0, 0, 0, true) G_STEP(ra0, rb0, 0, 1, true) G_STEP(ra0, rb0, 0, 2, true) G_STEP(ra0, rb0, 0, 3, true)
;     __syncthreads();
;     if (kt + 3 < nk) G_LOAD(ra0, rb0, (kt + 3) * 64)
;     G_STEP(ra1, rb1, 1, 0, more2) G_STEP(ra1, rb1, 1, 1, more2) G_STEP(ra1, rb1, 1, 2, more2) G_STEP(ra1, rb1, 1, 3, more2)
;     __syncthreads();
;   }
; DI void p3_qproj(KP p, int u, char* smem, int l) {
;     ...
; #pragma unroll
;       for (int r = 0; r < 16; ++r) {
;         const int ml = ml0 + crow(r, hh);
;         const int row = mt * 128 + ml;
;         float v = acc[i][j][r] * rs[ml];
;         if (rope) {
;           float sn, cs;
;           rope_consts(l31, row & 4095, sn, cs);
;           float pr = __shfl_xor(v, 8);
;           v = (l31 & 8) ? (v * cs + pr * sn) : (v * cs - pr * sn);
;         }
;         Q[(size_t)row * 768 + n0 + l31] = f2bf(v);
;       }
	v_mfma_f32_32x32x16_bf16 v[18:33], v[68:71], v[72:75], v[18:33]
	v_mfma_f32_32x32x16_bf16 v[2:17], v[68:71], v[76:79], v[2:17]
	ds_read_b128 v[68:71], v66 offset:36864
	ds_read_b128 v[72:75], v67 offset:55296
	ds_read_b128 v[76:79], v67 offset:59904
	s_waitcnt lgkmcnt(1)
	v_mfma_f32_32x32x16_bf16 v[50:65], v[68:71], v[72:75], v[50:65]
	s_waitcnt lgkmcnt(0)
	v_mfma_f32_32x32x16_bf16 v[34:49], v[68:71], v[76:79], v[34:49]
	ds_read_b128 v[68:71], v66 offset:41472
	s_waitcnt lgkmcnt(0)
	v_mfma_f32_32x32x16_bf16 v[18:33], v[68:71], v[72:75], v[18:33]
	v_mfma_f32_32x32x16_bf16 v[2:17], v[68:71], v[76:79], v[2:17]
	ds_read_b128 v[68:71], v66 offset:36896
	ds_read_b128 v[72:75], v67 offset:55328
	ds_read_b128 v[76:79], v67 offset:59936
	s_waitcnt lgkmcnt(1)
	v_mfma_f32_32x32x16_bf16 v[50:65], v[68:71], v[72:75], v[50:65]
	s_waitcnt lgkmcnt(0)
	v_mfma_f32_32x32x16_bf16 v[34:49], v[68:71], v[76:79], v[34:49]
	ds_read_b128 v[68:71], v66 offset:41504
	s_waitcnt lgkmcnt(0)
	v_mfma_f32_32x32x16_bf16 v[18:33], v[68:71], v[72:75], v[18:33]
	v_mfma_f32_32x32x16_bf16 v[2:17], v[68:71], v[76:79], v[2:17]
	ds_read_b128 v[70:73], v66 offset:36928
	ds_read_b128 v[74:77], v67 offset:55360
	ds_read_b128 v[78:81], v67 offset:59968
	ds_read_b128 v[82:85], v66 offset:41536
	v_and_or_b32 v68, v86, 64, s3
	s_mov_b32 s3, 0x2aaaaaab
	v_and_b32_e32 v69, 31, v88
	s_waitcnt lgkmcnt(2)
	v_mfma_f32_32x32x16_bf16 v[50:65], v[70:73], v[74:77], v[50:65]
	s_waitcnt lgkmcnt(1)
	v_mfma_f32_32x32x16_bf16 v[34:49], v[70:73], v[78:81], v[34:49]
	ds_read_b128 v[70:73], v66 offset:36960
	ds_read_b128 v[92:95], v66 offset:41568
	ds_read_b128 v[96:99], v67 offset:55392
	ds_read_b128 v[100:103], v67 offset:60000
	v_ashrrev_i32_e32 v66, 1, v86
	v_and_b32_e32 v89, 0xffffffc0, v66
	v_lshrrev_b32_e32 v66, 3, v88
	v_and_b32_e32 v90, 4, v66
	v_and_b32_e32 v66, 7, v88
	v_cvt_f32_ubyte0_e32 v66, v66
	s_waitcnt lgkmcnt(4)
	v_mfma_f32_32x32x16_bf16 v[18:33], v[82:85], v[74:77], v[18:33]
	v_mul_f32_e32 v66, 0xbfd49a78, v66
	v_exp_f32_e32 v86, v66
	v_xor_b32_e32 v66, 8, v219
	v_cmp_lt_i32_e32 vcc, v66, v87
	s_waitcnt lgkmcnt(0)
	s_barrier
	v_mfma_f32_32x32x16_bf16 v[2:17], v[82:85], v[78:81], v[2:17]
	v_cndmask_b32_e32 v66, v219, v66, vcc
	v_lshlrev_b32_e32 v87, 2, v66
	v_and_b32_e32 v66, 8, v88
	v_cmp_eq_u32_e32 vcc, 0, v66
	v_mul_hi_i32 v66, v68, s3
	v_lshrrev_b32_e32 v67, 31, v66
	v_lshrrev_b32_e32 v66, 4, v66
	v_mfma_f32_32x32x16_bf16 v[50:65], v[70:73], v[96:99], v[50:65]
	v_add_u32_e32 v66, v66, v67
	v_or_b32_e32 v67, v89, v90
	s_movk_i32 s3, 0x60
	v_mul_lo_u32 v66, v66, s3
	v_sub_u32_e32 v66, v68, v66
	v_cmp_eq_u32_e64 s[8:9], 64, v66
	v_mfma_f32_32x32x16_bf16 v[34:49], v[70:73], v[100:103], v[34:49]
	v_lshl_add_u32 v70, v67, 2, v234
	ds_read_b32 v104, v70
	v_add_u32_e32 v70, s2, v67
	s_and_b64 s[12:13], s[14:15], s[8:9]
	v_bfe_u32 v66, v70, 6, 6
	v_cmp_gt_u32_e64 s[8:9], 16, v69
	s_waitcnt lgkmcnt(0)
	v_mul_f32_e32 v50, v50, v104
	v_mfma_f32_32x32x16_bf16 v[18:33], v[92:95], v[96:99], v[18:33]
	v_cndmask_b32_e64 v105, v90, v66, s[8:9]
	v_mfma_f32_32x32x16_bf16 v[2:17], v[92:95], v[100:103], v[2:17]
	s_and_saveexec_b64 s[10:11], s[12:13]
	s_cbranch_execz .LBB0_737
	v_cvt_f32_ubyte0_e32 v66, v105
	v_mul_f32_e32 v66, v86, v66
	v_mul_f32_e32 v66, 0.15915494, v66
	v_mov_b32_dpp v67, v50 row_ror:8 row_mask:0xf bank_mask:0xf
	v_sin_f32_e32 v71, v66
	v_cos_f32_e32 v66, v66
	s_waitcnt lgkmcnt(0)
	v_mul_f32_e32 v67, v71, v67
	v_cndmask_b32_e64 v67, v67, -v67, vcc
	v_fmac_f32_e32 v67, v66, v50
	v_mov_b32_e32 v50, v67
.LBB0_737:
	s_or_b64 exec, exec, s[10:11]
	v_lshlrev_b32_e32 v198, 1, v69
	v_lshl_add_u64 v[66:67], s[6:7], 0, v[198:199]
	v_ashrrev_i32_e32 v69, 31, v68
	v_lshl_add_u64 v[66:67], v[68:69], 1, v[66:67]
	v_or_b32_e32 v69, 1, v90
	v_or_b32_e32 v72, v69, v89
	v_lshl_add_u32 v71, v72, 2, v234
	s_mov_b64 s[4:5], 0x8d50000
	ds_read_b32 v107, v71
	v_lshl_add_u64 v[66:67], v[66:67], 0, s[4:5]
	v_cvt_pk_bf16_f32 v50, v50, s0
	v_mad_i64_i32 v[70:71], s[4:5], v70, s44, v[66:67]
	global_store_short v[70:71], v50, off
	v_add_u32_e32 v50, s2, v72
	v_bfe_u32 v72, v50, 6, 6
	s_waitcnt lgkmcnt(0)
	v_mul_f32_e32 v51, v51, v107
	v_cndmask_b32_e64 v106, v69, v72, s[8:9]
	s_and_saveexec_b64 s[6:7], s[12:13]
	s_cbranch_execz .LBB0_739
	v_cvt_f32_ubyte0_e32 v72, v106
	v_mul_f32_e32 v72, v86, v72
	v_mul_f32_e32 v72, 0.15915494, v72
	v_mov_b32_dpp v73, v51 row_ror:8 row_mask:0xf bank_mask:0xf
	v_sin_f32_e32 v74, v72
	v_cos_f32_e32 v72, v72
	s_waitcnt lgkmcnt(0)
	v_mul_f32_e32 v73, v74, v73
	v_cndmask_b32_e64 v73, v73, -v73, vcc
	v_fmac_f32_e32 v73, v72, v51
	v_mov_b32_e32 v51, v73
.LBB0_739:
	s_or_b64 exec, exec, s[6:7]
	v_or_b32_e32 v88, 2, v90
	v_or_b32_e32 v73, v88, v89
	v_cvt_pk_bf16_f32 v72, v51, s0
	v_lshl_add_u32 v51, v73, 2, v234
	ds_read_b32 v109, v51
	v_mad_i64_i32 v[50:51], s[4:5], v50, s44, v[66:67]
	global_store_short v[50:51], v72, off
	v_add_u32_e32 v72, s2, v73
	v_bfe_u32 v73, v72, 6, 6
	s_waitcnt lgkmcnt(0)
	v_mul_f32_e32 v52, v52, v109
	v_cndmask_b32_e64 v108, v88, v73, s[8:9]
	s_and_saveexec_b64 s[6:7], s[12:13]
	s_cbranch_execz .LBB0_741
	v_cvt_f32_ubyte0_e32 v73, v108
	v_mul_f32_e32 v73, v86, v73
	v_mul_f32_e32 v73, 0.15915494, v73
	v_mov_b32_dpp v74, v52 row_ror:8 row_mask:0xf bank_mask:0xf
	v_sin_f32_e32 v75, v73
	v_cos_f32_e32 v73, v73
	s_waitcnt lgkmcnt(0)
	v_mul_f32_e32 v74, v75, v74
	v_cndmask_b32_e64 v74, v74, -v74, vcc
	v_fmac_f32_e32 v74, v73, v52
	v_mov_b32_e32 v52, v74
; DI int crow(int r, int hh) { return (r & 3) + 8 * (r >> 2) + 4 * hh; }
; DI void rope_consts(int e, int t, float& sn, float& cs) {
;   const int i8 = e & 7;
;   const float inv = __builtin_amdgcn_exp2f(-(float)i8 * 1.6609640474436813f);
;   const float pos = (e < 16) ? (float)(t >> 6) : (float)(t & 63);
;   const float rev = pos * inv * 0.15915494309189535f;
;   sn = __builtin_amdgcn_sinf(rev);
;   cs = __builtin_amdgcn_cosf(rev);
; }
; DI void p3_qproj(KP p, int u, char* smem, int l) {
;     ...
; #pragma unroll
;       for (int r = 0; r < 16; ++r) {
;         const int ml = ml0 + crow(r, hh);
;         const int row = mt * 128 + ml;
;         float v = acc[i][j][r] * rs[ml];
;         if (rope) {
;           float sn, cs;
;           rope_consts(l31, row & 4095, sn, cs);
;           float pr = __shfl_xor(v, 8);
;           v = (l31 & 8) ? (v * cs + pr * sn) : (v * cs - pr * sn);
;         }
;         Q[(size_t)row * 768 + n0 + l31] = f2bf(v);
;       }
.LBB0_741:
	s_or_b64 exec, exec, s[6:7]
	v_or_b32_e32 v91, 3, v90
	v_or_b32_e32 v74, v91, v89
	v_lshl_add_u32 v73, v74, 2, v234
	ds_read_b32 v111, v73
	v_cvt_pk_bf16_f32 v52, v52, s0
	v_mad_i64_i32 v[72:73], s[4:5], v72, s44, v[66:67]
	global_store_short v[72:73], v52, off
	v_add_u32_e32 v52, s2, v74
	v_bfe_u32 v74, v52, 6, 6
	s_waitcnt lgkmcnt(0)
	v_mul_f32_e32 v53, v53, v111
	v_cndmask_b32_e64 v110, v91, v74, s[8:9]
	s_and_saveexec_b64 s[6:7], s[12:13]
	s_cbranch_execz .LBB0_743
	v_cvt_f32_ubyte0_e32 v74, v110
	v_mul_f32_e32 v74, v86, v74
	v_mul_f32_e32 v74, 0.15915494, v74
	v_mov_b32_dpp v75, v53 row_ror:8 row_mask:0xf bank_mask:0xf
	v_sin_f32_e32 v76, v74
	v_cos_f32_e32 v74, v74
	s_waitcnt lgkmcnt(0)
	v_mul_f32_e32 v75, v76, v75
	v_cndmask_b32_e64 v75, v75, -v75, vcc
	v_fmac_f32_e32 v75, v74, v53
	v_mov_b32_e32 v53, v75
.LBB0_743:
	s_or_b64 exec, exec, s[6:7]
	v_or_b32_e32 v92, 8, v90
	v_or_b32_e32 v75, v92, v89
	v_cvt_pk_bf16_f32 v74, v53, s0
	v_lshl_add_u32 v53, v75, 2, v234
	ds_read_b32 v113, v53
	v_mad_i64_i32 v[52:53], s[4:5], v52, s44, v[66:67]
	global_store_short v[52:53], v74, off
	v_add_u32_e32 v74, s2, v75
	v_bfe_u32 v75, v74, 6, 6
	s_waitcnt lgkmcnt(0)
	v_mul_f32_e32 v54, v54, v113
	v_cndmask_b32_e64 v112, v92, v75, s[8:9]
	s_and_saveexec_b64 s[6:7], s[12:13]
	s_cbranch_execz .LBB0_745
	v_cvt_f32_ubyte0_e32 v75, v112
	v_mul_f32_e32 v75, v86, v75
	v_mul_f32_e32 v75, 0.15915494, v75
	v_mov_b32_dpp v76, v54 row_ror:8 row_mask:0xf bank_mask:0xf
	v_sin_f32_e32 v77, v75
	v_cos_f32_e32 v75, v75
	s_waitcnt lgkmcnt(0)
	v_mul_f32_e32 v76, v77, v76
	v_cndmask_b32_e64 v76, v76, -v76, vcc
	v_fmac_f32_e32 v76, v75, v54
	v_mov_b32_e32 v54, v76
.LBB0_745:
	s_or_b64 exec, exec, s[6:7]
	v_or_b32_e32 v93, 9, v90
	v_or_b32_e32 v76, v93, v89
	v_lshl_add_u32 v75, v76, 2, v234
	ds_read_b32 v115, v75
	v_cvt_pk_bf16_f32 v54, v54, s0
	v_mad_i64_i32 v[74:75], s[4:5], v74, s44, v[66:67]
	global_store_short v[74:75], v54, off
	v_add_u32_e32 v54, s2, v76
	v_bfe_u32 v76, v54, 6, 6
	s_waitcnt lgkmcnt(0)
	v_mul_f32_e32 v55, v55, v115
	v_cndmask_b32_e64 v114, v93, v76, s[8:9]
	s_and_saveexec_b64 s[6:7], s[12:13]
	s_cbranch_execz .LBB0_747
	v_cvt_f32_ubyte0_e32 v76, v114
	v_mul_f32_e32 v76, v86, v76
	v_mul_f32_e32 v76, 0.15915494, v76
	v_mov_b32_dpp v77, v55 row_ror:8 row_mask:0xf bank_mask:0xf
	v_sin_f32_e32 v78, v76
	v_cos_f32_e32 v76, v76
	s_waitcnt lgkmcnt(0)
	v_mul_f32_e32 v77, v78, v77
	v_cndmask_b32_e64 v77, v77, -v77, vcc
	v_fmac_f32_e32 v77, v76, v55
	v_mov_b32_e32 v55, v77
.LBB0_747:
	s_or_b64 exec, exec, s[6:7]
	v_or_b32_e32 v94, 10, v90
	v_or_b32_e32 v77, v94, v89
	v_cvt_pk_bf16_f32 v76, v55, s0
	v_lshl_add_u32 v55, v77, 2, v234
	ds_read_b32 v117, v55
	v_mad_i64_i32 v[54:55], s[4:5], v54, s44, v[66:67]
	global_store_short v[54:55], v76, off
	v_add_u32_e32 v76, s2, v77
	v_bfe_u32 v77, v76, 6, 6
	s_waitcnt lgkmcnt(0)
	v_mul_f32_e32 v56, v56, v117
	v_cndmask_b32_e64 v116, v94, v77, s[8:9]
	s_and_saveexec_b64 s[6:7], s[12:13]
	s_cbranch_execz .LBB0_749
	v_cvt_f32_ubyte0_e32 v77, v116
	v_mul_f32_e32 v77, v86, v77
	v_mul_f32_e32 v77, 0.15915494, v77
	v_mov_b32_dpp v78, v56 row_ror:8 row_mask:0xf bank_mask:0xf
	v_sin_f32_e32 v79, v77
	v_cos_f32_e32 v77, v77
	s_waitcnt lgkmcnt(0)
	v_mul_f32_e32 v78, v79, v78
	v_cndmask_b32_e64 v78, v78, -v78, vcc
	v_fmac_f32_e32 v78, v77, v56
	v_mov_b32_e32 v56, v78
.LBB0_749:
	s_or_b64 exec, exec, s[6:7]
	v_or_b32_e32 v95, 11, v90
	v_or_b32_e32 v78, v95, v89
	v_lshl_add_u32 v77, v78, 2, v234
	ds_read_b32 v119, v77
	v_cvt_pk_bf16_f32 v56, v56, s0
	v_mad_i64_i32 v[76:77], s[4:5], v76, s44, v[66:67]
	global_store_short v[76:77], v56, off
	v_add_u32_e32 v56, s2, v78
	v_bfe_u32 v78, v56, 6, 6
	s_waitcnt lgkmcnt(0)
	v_mul_f32_e32 v57, v57, v119
	v_cndmask_b32_e64 v118, v95, v78, s[8:9]
	s_and_saveexec_b64 s[6:7], s[12:13]
	s_cbranch_execz .LBB0_751
	v_cvt_f32_ubyte0_e32 v78, v118
	v_mul_f32_e32 v78, v86, v78
	v_mul_f32_e32 v78, 0.15915494, v78
	v_mov_b32_dpp v79, v57 row_ror:8 row_mask:0xf bank_mask:0xf
	v_sin_f32_e32 v80, v78
	v_cos_f32_e32 v78, v78
	s_waitcnt lgkmcnt(0)
	v_mul_f32_e32 v79, v80, v79
	v_cndmask_b32_e64 v79, v79, -v79, vcc
	v_fmac_f32_e32 v79, v78, v57
	v_mov_b32_e32 v57, v79
.LBB0_751:
	s_or_b64 exec, exec, s[6:7]
	v_or_b32_e32 v96, 16, v90
	v_or_b32_e32 v79, v96, v89
	v_cvt_pk_bf16_f32 v78, v57, s0
	v_lshl_add_u32 v57, v79, 2, v234
	ds_read_b32 v121, v57
	v_mad_i64_i32 v[56:57], s[4:5], v56, s44, v[66:67]
	global_store_short v[56:57], v78, off
	v_add_u32_e32 v78, s2, v79
	v_bfe_u32 v79, v78, 6, 6
	s_waitcnt lgkmcnt(0)
	v_mul_f32_e32 v58, v58, v121
	v_cndmask_b32_e64 v120, v96, v79, s[8:9]
	s_and_saveexec_b64 s[6:7], s[12:13]
	s_cbranch_execz .LBB0_753
	v_cvt_f32_ubyte0_e32 v79, v120
	v_mul_f32_e32 v79, v86, v79
	v_mul_f32_e32 v79, 0.15915494, v79
	v_mov_b32_dpp v80, v58 row_ror:8 row_mask:0xf bank_mask:0xf
	v_sin_f32_e32 v81, v79
	v_cos_f32_e32 v79, v79
	s_waitcnt lgkmcnt(0)
	v_mul_f32_e32 v80, v81, v80
	v_cndmask_b32_e64 v80, v80, -v80, vcc
	v_fmac_f32_e32 v80, v79, v58
	v_mov_b32_e32 v58, v80
.LBB0_753:
	s_or_b64 exec, exec, s[6:7]
	v_or_b32_e32 v97, 17, v90
	v_or_b32_e32 v80, v97, v89
	v_lshl_add_u32 v79, v80, 2, v234
	ds_read_b32 v123, v79
	v_cvt_pk_bf16_f32 v58, v58, s0
	v_mad_i64_i32 v[78:79], s[4:5], v78, s44, v[66:67]
	global_store_short v[78:79], v58, off
	v_add_u32_e32 v58, s2, v80
	v_bfe_u32 v80, v58, 6, 6
	s_waitcnt lgkmcnt(0)
	v_mul_f32_e32 v59, v59, v123
	v_cndmask_b32_e64 v122, v97, v80, s[8:9]
	s_and_saveexec_b64 s[6:7], s[12:13]
	s_cbranch_execz .LBB0_755
	v_cvt_f32_ubyte0_e32 v80, v122
	v_mul_f32_e32 v80, v86, v80
	v_mul_f32_e32 v80, 0.15915494, v80
	v_mov_b32_dpp v81, v59 row_ror:8 row_mask:0xf bank_mask:0xf
	v_sin_f32_e32 v82, v80
	v_cos_f32_e32 v80, v80
	s_waitcnt lgkmcnt(0)
	v_mul_f32_e32 v81, v82, v81
	v_cndmask_b32_e64 v81, v81, -v81, vcc
	v_fmac_f32_e32 v81, v80, v59
	v_mov_b32_e32 v59, v81
; DI int crow(int r, int hh) { return (r & 3) + 8 * (r >> 2) + 4 * hh; }
; DI void rope_consts(int e, int t, float& sn, float& cs) {
;   const int i8 = e & 7;
;   const float inv = __builtin_amdgcn_exp2f(-(float)i8 * 1.6609640474436813f);
;   const float pos = (e < 16) ? (float)(t >> 6) : (float)(t & 63);
;   const float rev = pos * inv * 0.15915494309189535f;
;   sn = __builtin_amdgcn_sinf(rev);
;   cs = __builtin_amdgcn_cosf(rev);
; }
; DI void p3_qproj(KP p, int u, char* smem, int l) {
;     ...
; #pragma unroll
;       for (int r = 0; r < 16; ++r) {
;         const int ml = ml0 + crow(r, hh);
;         const int row = mt * 128 + ml;
;         float v = acc[i][j][r] * rs[ml];
;         if (rope) {
;           float sn, cs;
;           rope_consts(l31, row & 4095, sn, cs);
;           float pr = __shfl_xor(v, 8);
;           v = (l31 & 8) ? (v * cs + pr * sn) : (v * cs - pr * sn);
;         }
;         Q[(size_t)row * 768 + n0 + l31] = f2bf(v);
;       }
.LBB0_755:
	s_or_b64 exec, exec, s[6:7]
	v_or_b32_e32 v98, 18, v90
	v_or_b32_e32 v81, v98, v89
	v_cvt_pk_bf16_f32 v80, v59, s0
	v_lshl_add_u32 v59, v81, 2, v234
	ds_read_b32 v125, v59
	v_mad_i64_i32 v[58:59], s[4:5], v58, s44, v[66:67]
	global_store_short v[58:59], v80, off
	v_add_u32_e32 v80, s2, v81
	v_bfe_u32 v81, v80, 6, 6
	s_waitcnt lgkmcnt(0)
	v_mul_f32_e32 v60, v60, v125
	v_cndmask_b32_e64 v124, v98, v81, s[8:9]
	s_and_saveexec_b64 s[6:7], s[12:13]
	s_cbranch_execz .LBB0_757
	v_cvt_f32_ubyte0_e32 v81, v124
	v_mul_f32_e32 v81, v86, v81
	v_mul_f32_e32 v81, 0.15915494, v81
	v_mov_b32_dpp v82, v60 row_ror:8 row_mask:0xf bank_mask:0xf
	v_sin_f32_e32 v83, v81
	v_cos_f32_e32 v81, v81
	s_waitcnt lgkmcnt(0)
	v_mul_f32_e32 v82, v83, v82
	v_cndmask_b32_e64 v82, v82, -v82, vcc
	v_fmac_f32_e32 v82, v81, v60
	v_mov_b32_e32 v60, v82
.LBB0_757:
	s_or_b64 exec, exec, s[6:7]
	v_or_b32_e32 v99, 19, v90
	v_or_b32_e32 v82, v99, v89
	v_lshl_add_u32 v81, v82, 2, v234
	ds_read_b32 v127, v81
	v_cvt_pk_bf16_f32 v60, v60, s0
	v_mad_i64_i32 v[80:81], s[4:5], v80, s44, v[66:67]
	global_store_short v[80:81], v60, off
	v_add_u32_e32 v60, s2, v82
	v_bfe_u32 v82, v60, 6, 6
	s_waitcnt lgkmcnt(0)
	v_mul_f32_e32 v61, v61, v127
	v_cndmask_b32_e64 v126, v99, v82, s[8:9]
	s_and_saveexec_b64 s[6:7], s[12:13]
	s_cbranch_execz .LBB0_759
	v_cvt_f32_ubyte0_e32 v82, v126
	v_mul_f32_e32 v82, v86, v82
	v_mul_f32_e32 v82, 0.15915494, v82
	v_mov_b32_dpp v83, v61 row_ror:8 row_mask:0xf bank_mask:0xf
	v_sin_f32_e32 v84, v82
	v_cos_f32_e32 v82, v82
	s_waitcnt lgkmcnt(0)
	v_mul_f32_e32 v83, v84, v83
	v_cndmask_b32_e64 v83, v83, -v83, vcc
	v_fmac_f32_e32 v83, v82, v61
	v_mov_b32_e32 v61, v83
.LBB0_759:
	s_or_b64 exec, exec, s[6:7]
	v_or_b32_e32 v100, 24, v90
	v_or_b32_e32 v83, v100, v89
	v_cvt_pk_bf16_f32 v82, v61, s0
	v_lshl_add_u32 v61, v83, 2, v234
	ds_read_b32 v129, v61
	v_mad_i64_i32 v[60:61], s[4:5], v60, s44, v[66:67]
	global_store_short v[60:61], v82, off
	v_add_u32_e32 v82, s2, v83
	v_bfe_u32 v83, v82, 6, 6
	s_waitcnt lgkmcnt(0)
	v_mul_f32_e32 v62, v62, v129
	v_cndmask_b32_e64 v128, v100, v83, s[8:9]
	s_and_saveexec_b64 s[6:7], s[12:13]
	s_cbranch_execz .LBB0_761
	v_cvt_f32_ubyte0_e32 v83, v128
	v_mul_f32_e32 v83, v86, v83
	v_mul_f32_e32 v83, 0.15915494, v83
	v_mov_b32_dpp v84, v62 row_ror:8 row_mask:0xf bank_mask:0xf
	v_sin_f32_e32 v85, v83
	v_cos_f32_e32 v83, v83
	s_waitcnt lgkmcnt(0)
	v_mul_f32_e32 v84, v85, v84
	v_cndmask_b32_e64 v84, v84, -v84, vcc
	v_fmac_f32_e32 v84, v83, v62
	v_mov_b32_e32 v62, v84
.LBB0_761:
	s_or_b64 exec, exec, s[6:7]
	v_or_b32_e32 v101, 25, v90
	v_or_b32_e32 v84, v101, v89
	v_lshl_add_u32 v83, v84, 2, v234
	ds_read_b32 v131, v83
	v_cvt_pk_bf16_f32 v62, v62, s0
	v_mad_i64_i32 v[82:83], s[4:5], v82, s44, v[66:67]
	global_store_short v[82:83], v62, off
	v_add_u32_e32 v62, s2, v84
	v_bfe_u32 v84, v62, 6, 6
	s_waitcnt lgkmcnt(0)
	v_mul_f32_e32 v63, v63, v131
	v_cndmask_b32_e64 v130, v101, v84, s[8:9]
	s_and_saveexec_b64 s[6:7], s[12:13]
	s_cbranch_execz .LBB0_763
	v_cvt_f32_ubyte0_e32 v84, v130
	v_mul_f32_e32 v84, v86, v84
	v_mul_f32_e32 v84, 0.15915494, v84
	v_mov_b32_dpp v85, v63 row_ror:8 row_mask:0xf bank_mask:0xf
	v_sin_f32_e32 v102, v84
	v_cos_f32_e32 v84, v84
	s_waitcnt lgkmcnt(0)
	v_mul_f32_e32 v85, v102, v85
	v_cndmask_b32_e64 v85, v85, -v85, vcc
	v_fmac_f32_e32 v85, v84, v63
	v_mov_b32_e32 v63, v85
.LBB0_763:
	s_or_b64 exec, exec, s[6:7]
	v_or_b32_e32 v102, 26, v90
	v_or_b32_e32 v85, v102, v89
	v_cvt_pk_bf16_f32 v84, v63, s0
	v_lshl_add_u32 v63, v85, 2, v234
	ds_read_b32 v133, v63
	v_mad_i64_i32 v[62:63], s[4:5], v62, s44, v[66:67]
	global_store_short v[62:63], v84, off
	v_add_u32_e32 v84, s2, v85
	v_bfe_u32 v85, v84, 6, 6
	s_waitcnt lgkmcnt(0)
	v_mul_f32_e32 v64, v64, v133
	v_cndmask_b32_e64 v132, v102, v85, s[8:9]
	s_and_saveexec_b64 s[6:7], s[12:13]
	s_cbranch_execz .LBB0_765
	v_cvt_f32_ubyte0_e32 v85, v132
	v_mul_f32_e32 v85, v86, v85
	v_mul_f32_e32 v85, 0.15915494, v85
	v_mov_b32_dpp v103, v64 row_ror:8 row_mask:0xf bank_mask:0xf
	v_sin_f32_e32 v134, v85
	v_cos_f32_e32 v85, v85
	s_waitcnt lgkmcnt(0)
	v_mul_f32_e32 v103, v134, v103
	v_cndmask_b32_e64 v103, v103, -v103, vcc
	v_fmac_f32_e32 v103, v85, v64
	v_mov_b32_e32 v64, v103
.LBB0_765:
	s_or_b64 exec, exec, s[6:7]
	v_or_b32_e32 v103, 27, v90
	v_or_b32_e32 v134, v103, v89
	v_lshl_add_u32 v85, v134, 2, v234
	ds_read_b32 v135, v85
	v_cvt_pk_bf16_f32 v64, v64, s0
	v_mad_i64_i32 v[84:85], s[4:5], v84, s44, v[66:67]
	global_store_short v[84:85], v64, off
	v_add_u32_e32 v64, s2, v134
	v_bfe_u32 v134, v64, 6, 6
	s_waitcnt lgkmcnt(0)
	v_mul_f32_e32 v65, v65, v135
	v_cndmask_b32_e64 v134, v103, v134, s[8:9]
	s_and_saveexec_b64 s[6:7], s[12:13]
	s_cbranch_execz .LBB0_767
	v_cvt_f32_ubyte0_e32 v136, v134
	v_mul_f32_e32 v136, v86, v136
	v_mul_f32_e32 v136, 0.15915494, v136
	v_mov_b32_dpp v137, v65 row_ror:8 row_mask:0xf bank_mask:0xf
	v_sin_f32_e32 v138, v136
	v_cos_f32_e32 v136, v136
	s_waitcnt lgkmcnt(0)
	v_mul_f32_e32 v137, v138, v137
	v_cndmask_b32_e64 v137, v137, -v137, vcc
	v_fmac_f32_e32 v137, v136, v65
	v_mov_b32_e32 v65, v137
.LBB0_767:
	s_or_b64 exec, exec, s[6:7]
	v_cvt_pk_bf16_f32 v136, v65, s0
	v_mad_i64_i32 v[64:65], s[4:5], v64, s44, v[66:67]
	v_or_b32_e32 v68, 32, v68
	s_mov_b32 s3, 0x2aaaaaab
	global_store_short v[64:65], v136, off
	v_mul_hi_i32 v136, v68, s3
	v_lshrrev_b32_e32 v137, 31, v136
	v_lshrrev_b32_e32 v136, 4, v136
	v_add_u32_e32 v136, v136, v137
	s_movk_i32 s3, 0x60
	v_mul_lo_u32 v136, v136, s3
	v_sub_u32_e32 v68, v68, v136
	v_cmp_eq_u32_e64 s[10:11], 64, v68
	s_and_b64 s[6:7], s[14:15], s[10:11]
	v_mul_f32_e32 v34, v34, v104
	s_and_saveexec_b64 s[10:11], s[6:7]
	s_cbranch_execz .LBB0_769
	v_cvt_f32_ubyte0_e32 v68, v105
	v_mul_f32_e32 v68, v86, v68
	v_mul_f32_e32 v68, 0.15915494, v68
	v_mov_b32_dpp v104, v34 row_ror:8 row_mask:0xf bank_mask:0xf
	v_sin_f32_e32 v105, v68
	v_cos_f32_e32 v68, v68
	s_waitcnt lgkmcnt(0)
	v_mul_f32_e32 v104, v105, v104
	v_cndmask_b32_e64 v104, v104, -v104, vcc
	v_fmac_f32_e32 v104, v68, v34
	v_mov_b32_e32 v34, v104
; DI int crow(int r, int hh) { return (r & 3) + 8 * (r >> 2) + 4 * hh; }
; DI void rope_consts(int e, int t, float& sn, float& cs) {
;   const int i8 = e & 7;
;   const float inv = __builtin_amdgcn_exp2f(-(float)i8 * 1.6609640474436813f);
;   const float pos = (e < 16) ? (float)(t >> 6) : (float)(t & 63);
;   const float rev = pos * inv * 0.15915494309189535f;
;   sn = __builtin_amdgcn_sinf(rev);
;   cs = __builtin_amdgcn_cosf(rev);
; }
; DI void p3_qproj(KP p, int u, char* smem, int l) {
;     ...
; #pragma unroll
;       for (int r = 0; r < 16; ++r) {
;         const int ml = ml0 + crow(r, hh);
;         const int row = mt * 128 + ml;
;         float v = acc[i][j][r] * rs[ml];
;         if (rope) {
;           float sn, cs;
;           rope_consts(l31, row & 4095, sn, cs);
;           float pr = __shfl_xor(v, 8);
;           v = (l31 & 8) ? (v * cs + pr * sn) : (v * cs - pr * sn);
;         }
;         Q[(size_t)row * 768 + n0 + l31] = f2bf(v);
;       }
.LBB0_769:
	s_or_b64 exec, exec, s[10:11]
	v_cvt_pk_bf16_f32 v34, v34, s0
	global_store_short v[70:71], v34, off offset:64
	v_mul_f32_e32 v34, v35, v107
	s_and_saveexec_b64 s[10:11], s[6:7]
	s_cbranch_execz .LBB0_771
	v_cvt_f32_ubyte0_e32 v35, v106
	v_mul_f32_e32 v35, v86, v35
	v_mul_f32_e32 v35, 0.15915494, v35
	v_mov_b32_dpp v68, v34 row_ror:8 row_mask:0xf bank_mask:0xf
	v_sin_f32_e32 v70, v35
	v_cos_f32_e32 v35, v35
	s_waitcnt lgkmcnt(0)
	v_mul_f32_e32 v68, v70, v68
	v_cndmask_b32_e64 v68, v68, -v68, vcc
	v_fmac_f32_e32 v68, v35, v34
	v_mov_b32_e32 v34, v68
.LBB0_771:
	s_or_b64 exec, exec, s[10:11]
	v_cvt_pk_bf16_f32 v34, v34, s0
	global_store_short v[50:51], v34, off offset:64
	v_mul_f32_e32 v34, v36, v109
	s_and_saveexec_b64 s[10:11], s[6:7]
	s_cbranch_execz .LBB0_773
	v_cvt_f32_ubyte0_e32 v35, v108
	v_mul_f32_e32 v35, v86, v35
	v_mul_f32_e32 v35, 0.15915494, v35
	v_mov_b32_dpp v36, v34 row_ror:8 row_mask:0xf bank_mask:0xf
	v_sin_f32_e32 v50, v35
	v_cos_f32_e32 v35, v35
	s_waitcnt lgkmcnt(0)
	v_mul_f32_e32 v36, v50, v36
	v_cndmask_b32_e64 v36, v36, -v36, vcc
	v_fmac_f32_e32 v36, v35, v34
	v_mov_b32_e32 v34, v36
.LBB0_773:
	s_or_b64 exec, exec, s[10:11]
	v_cvt_pk_bf16_f32 v34, v34, s0
	global_store_short v[72:73], v34, off offset:64
	v_mul_f32_e32 v34, v37, v111
	s_and_saveexec_b64 s[10:11], s[6:7]
	s_cbranch_execz .LBB0_775
	v_cvt_f32_ubyte0_e32 v35, v110
	v_mul_f32_e32 v35, v86, v35
	v_mul_f32_e32 v35, 0.15915494, v35
	v_mov_b32_dpp v36, v34 row_ror:8 row_mask:0xf bank_mask:0xf
	v_sin_f32_e32 v37, v35
	v_cos_f32_e32 v35, v35
	s_waitcnt lgkmcnt(0)
	v_mul_f32_e32 v36, v37, v36
	v_cndmask_b32_e64 v36, v36, -v36, vcc
	v_fmac_f32_e32 v36, v35, v34
	v_mov_b32_e32 v34, v36
.LBB0_775:
	s_or_b64 exec, exec, s[10:11]
	v_cvt_pk_bf16_f32 v34, v34, s0
	global_store_short v[52:53], v34, off offset:64
	v_mul_f32_e32 v34, v38, v113
	s_and_saveexec_b64 s[10:11], s[6:7]
	s_cbranch_execz .LBB0_777
	v_cvt_f32_ubyte0_e32 v35, v112
	v_mul_f32_e32 v35, v86, v35
	v_mul_f32_e32 v35, 0.15915494, v35
	v_mov_b32_dpp v36, v34 row_ror:8 row_mask:0xf bank_mask:0xf
	v_sin_f32_e32 v37, v35
	v_cos_f32_e32 v35, v35
	s_waitcnt lgkmcnt(0)
	v_mul_f32_e32 v36, v37, v36
	v_cndmask_b32_e64 v36, v36, -v36, vcc
	v_fmac_f32_e32 v36, v35, v34
	v_mov_b32_e32 v34, v36
.LBB0_777:
	s_or_b64 exec, exec, s[10:11]
	v_cvt_pk_bf16_f32 v34, v34, s0
	global_store_short v[74:75], v34, off offset:64
	v_mul_f32_e32 v34, v39, v115
	s_and_saveexec_b64 s[10:11], s[6:7]
	s_cbranch_execz .LBB0_779
	v_cvt_f32_ubyte0_e32 v35, v114
	v_mul_f32_e32 v35, v86, v35
	v_mul_f32_e32 v35, 0.15915494, v35
	v_mov_b32_dpp v36, v34 row_ror:8 row_mask:0xf bank_mask:0xf
	v_sin_f32_e32 v37, v35
	v_cos_f32_e32 v35, v35
	s_waitcnt lgkmcnt(0)
	v_mul_f32_e32 v36, v37, v36
	v_cndmask_b32_e64 v36, v36, -v36, vcc
	v_fmac_f32_e32 v36, v35, v34
	v_mov_b32_e32 v34, v36
.LBB0_779:
	s_or_b64 exec, exec, s[10:11]
	v_cvt_pk_bf16_f32 v34, v34, s0
	global_store_short v[54:55], v34, off offset:64
	v_mul_f32_e32 v34, v40, v117
	s_and_saveexec_b64 s[10:11], s[6:7]
	s_cbranch_execz .LBB0_781
	v_cvt_f32_ubyte0_e32 v35, v116
	v_mul_f32_e32 v35, v86, v35
	v_mul_f32_e32 v35, 0.15915494, v35
	v_mov_b32_dpp v36, v34 row_ror:8 row_mask:0xf bank_mask:0xf
	v_sin_f32_e32 v37, v35
	v_cos_f32_e32 v35, v35
	s_waitcnt lgkmcnt(0)
	v_mul_f32_e32 v36, v37, v36
	v_cndmask_b32_e64 v36, v36, -v36, vcc
	v_fmac_f32_e32 v36, v35, v34
	v_mov_b32_e32 v34, v36
.LBB0_781:
	s_or_b64 exec, exec, s[10:11]
	v_cvt_pk_bf16_f32 v34, v34, s0
	global_store_short v[76:77], v34, off offset:64
	v_mul_f32_e32 v34, v41, v119
	s_and_saveexec_b64 s[10:11], s[6:7]
	s_cbranch_execz .LBB0_783
	v_cvt_f32_ubyte0_e32 v35, v118
	v_mul_f32_e32 v35, v86, v35
	v_mul_f32_e32 v35, 0.15915494, v35
	v_mov_b32_dpp v36, v34 row_ror:8 row_mask:0xf bank_mask:0xf
	v_sin_f32_e32 v37, v35
	v_cos_f32_e32 v35, v35
	s_waitcnt lgkmcnt(0)
	v_mul_f32_e32 v36, v37, v36
	v_cndmask_b32_e64 v36, v36, -v36, vcc
	v_fmac_f32_e32 v36, v35, v34
	v_mov_b32_e32 v34, v36
.LBB0_783:
	s_or_b64 exec, exec, s[10:11]
	v_cvt_pk_bf16_f32 v34, v34, s0
	global_store_short v[56:57], v34, off offset:64
	v_mul_f32_e32 v34, v42, v121
	s_and_saveexec_b64 s[10:11], s[6:7]
	s_cbranch_execz .LBB0_785
	v_cvt_f32_ubyte0_e32 v35, v120
	v_mul_f32_e32 v35, v86, v35
	v_mul_f32_e32 v35, 0.15915494, v35
	v_mov_b32_dpp v36, v34 row_ror:8 row_mask:0xf bank_mask:0xf
	v_sin_f32_e32 v37, v35
	v_cos_f32_e32 v35, v35
	s_waitcnt lgkmcnt(0)
	v_mul_f32_e32 v36, v37, v36
	v_cndmask_b32_e64 v36, v36, -v36, vcc
	v_fmac_f32_e32 v36, v35, v34
	v_mov_b32_e32 v34, v36
.LBB0_785:
	s_or_b64 exec, exec, s[10:11]
	v_cvt_pk_bf16_f32 v34, v34, s0
	global_store_short v[78:79], v34, off offset:64
	v_mul_f32_e32 v34, v43, v123
	s_and_saveexec_b64 s[10:11], s[6:7]
	s_cbranch_execz .LBB0_787
	v_cvt_f32_ubyte0_e32 v35, v122
	v_mul_f32_e32 v35, v86, v35
	v_mul_f32_e32 v35, 0.15915494, v35
	v_mov_b32_dpp v36, v34 row_ror:8 row_mask:0xf bank_mask:0xf
	v_sin_f32_e32 v37, v35
	v_cos_f32_e32 v35, v35
	s_waitcnt lgkmcnt(0)
	v_mul_f32_e32 v36, v37, v36
	v_cndmask_b32_e64 v36, v36, -v36, vcc
	v_fmac_f32_e32 v36, v35, v34
	v_mov_b32_e32 v34, v36
.LBB0_787:
	s_or_b64 exec, exec, s[10:11]
	v_cvt_pk_bf16_f32 v34, v34, s0
	global_store_short v[58:59], v34, off offset:64
	v_mul_f32_e32 v34, v44, v125
	s_and_saveexec_b64 s[10:11], s[6:7]
	s_cbranch_execz .LBB0_789
	v_cvt_f32_ubyte0_e32 v35, v124
	v_mul_f32_e32 v35, v86, v35
	v_mul_f32_e32 v35, 0.15915494, v35
	v_mov_b32_dpp v36, v34 row_ror:8 row_mask:0xf bank_mask:0xf
	v_sin_f32_e32 v37, v35
	v_cos_f32_e32 v35, v35
	s_waitcnt lgkmcnt(0)
	v_mul_f32_e32 v36, v37, v36
	v_cndmask_b32_e64 v36, v36, -v36, vcc
	v_fmac_f32_e32 v36, v35, v34
	v_mov_b32_e32 v34, v36
; DI int crow(int r, int hh) { return (r & 3) + 8 * (r >> 2) + 4 * hh; }
; DI void rope_consts(int e, int t, float& sn, float& cs) {
;   const int i8 = e & 7;
;   const float inv = __builtin_amdgcn_exp2f(-(float)i8 * 1.6609640474436813f);
;   const float pos = (e < 16) ? (float)(t >> 6) : (float)(t & 63);
;   const float rev = pos * inv * 0.15915494309189535f;
;   sn = __builtin_amdgcn_sinf(rev);
;   cs = __builtin_amdgcn_cosf(rev);
; }
; DI void p3_qproj(KP p, int u, char* smem, int l) {
;     ...
; #pragma unroll
;       for (int r = 0; r < 16; ++r) {
;         const int ml = ml0 + crow(r, hh);
;         const int row = mt * 128 + ml;
;         float v = acc[i][j][r] * rs[ml];
;         if (rope) {
;           float sn, cs;
;           rope_consts(l31, row & 4095, sn, cs);
;           float pr = __shfl_xor(v, 8);
;           v = (l31 & 8) ? (v * cs + pr * sn) : (v * cs - pr * sn);
;         }
;         Q[(size_t)row * 768 + n0 + l31] = f2bf(v);
;       }
.LBB0_789:
	s_or_b64 exec, exec, s[10:11]
	v_cvt_pk_bf16_f32 v34, v34, s0
	global_store_short v[80:81], v34, off offset:64
	v_mul_f32_e32 v34, v45, v127
	s_and_saveexec_b64 s[10:11], s[6:7]
	s_cbranch_execz .LBB0_791
	v_cvt_f32_ubyte0_e32 v35, v126
	v_mul_f32_e32 v35, v86, v35
	v_mul_f32_e32 v35, 0.15915494, v35
	v_mov_b32_dpp v36, v34 row_ror:8 row_mask:0xf bank_mask:0xf
	v_sin_f32_e32 v37, v35
	v_cos_f32_e32 v35, v35
	s_waitcnt lgkmcnt(0)
	v_mul_f32_e32 v36, v37, v36
	v_cndmask_b32_e64 v36, v36, -v36, vcc
	v_fmac_f32_e32 v36, v35, v34
	v_mov_b32_e32 v34, v36
.LBB0_791:
	s_or_b64 exec, exec, s[10:11]
	v_cvt_pk_bf16_f32 v34, v34, s0
	global_store_short v[60:61], v34, off offset:64
	v_mul_f32_e32 v34, v46, v129
	s_and_saveexec_b64 s[10:11], s[6:7]
	s_cbranch_execz .LBB0_793
	v_cvt_f32_ubyte0_e32 v35, v128
	v_mul_f32_e32 v35, v86, v35
	v_mul_f32_e32 v35, 0.15915494, v35
	v_mov_b32_dpp v36, v34 row_ror:8 row_mask:0xf bank_mask:0xf
	v_sin_f32_e32 v37, v35
	v_cos_f32_e32 v35, v35
	s_waitcnt lgkmcnt(0)
	v_mul_f32_e32 v36, v37, v36
	v_cndmask_b32_e64 v36, v36, -v36, vcc
	v_fmac_f32_e32 v36, v35, v34
	v_mov_b32_e32 v34, v36
.LBB0_793:
	s_or_b64 exec, exec, s[10:11]
	v_cvt_pk_bf16_f32 v34, v34, s0
	global_store_short v[82:83], v34, off offset:64
	v_mul_f32_e32 v34, v47, v131
	s_and_saveexec_b64 s[10:11], s[6:7]
	s_cbranch_execz .LBB0_795
	v_cvt_f32_ubyte0_e32 v35, v130
	v_mul_f32_e32 v35, v86, v35
	v_mul_f32_e32 v35, 0.15915494, v35
	v_mov_b32_dpp v36, v34 row_ror:8 row_mask:0xf bank_mask:0xf
	v_sin_f32_e32 v37, v35
	v_cos_f32_e32 v35, v35
	s_waitcnt lgkmcnt(0)
	v_mul_f32_e32 v36, v37, v36
	v_cndmask_b32_e64 v36, v36, -v36, vcc
	v_fmac_f32_e32 v36, v35, v34
	v_mov_b32_e32 v34, v36
.LBB0_795:
	s_or_b64 exec, exec, s[10:11]
	v_cvt_pk_bf16_f32 v34, v34, s0
	global_store_short v[62:63], v34, off offset:64
	v_mul_f32_e32 v34, v48, v133
	s_and_saveexec_b64 s[10:11], s[6:7]
	s_cbranch_execz .LBB0_797
	v_cvt_f32_ubyte0_e32 v35, v132
	v_mul_f32_e32 v35, v86, v35
	v_mul_f32_e32 v35, 0.15915494, v35
	v_mov_b32_dpp v36, v34 row_ror:8 row_mask:0xf bank_mask:0xf
	v_sin_f32_e32 v37, v35
	v_cos_f32_e32 v35, v35
	s_waitcnt lgkmcnt(0)
	v_mul_f32_e32 v36, v37, v36
	v_cndmask_b32_e64 v36, v36, -v36, vcc
	v_fmac_f32_e32 v36, v35, v34
	v_mov_b32_e32 v34, v36
.LBB0_797:
	s_or_b64 exec, exec, s[10:11]
	v_cvt_pk_bf16_f32 v34, v34, s0
	global_store_short v[84:85], v34, off offset:64
	v_mul_f32_e32 v34, v49, v135
	s_and_saveexec_b64 s[10:11], s[6:7]
	s_cbranch_execz .LBB0_799
	v_cvt_f32_ubyte0_e32 v35, v134
	v_mul_f32_e32 v35, v86, v35
	v_mul_f32_e32 v35, 0.15915494, v35
	v_mov_b32_dpp v36, v34 row_ror:8 row_mask:0xf bank_mask:0xf
	v_sin_f32_e32 v37, v35
	v_cos_f32_e32 v35, v35
	s_waitcnt lgkmcnt(0)
	v_mul_f32_e32 v36, v37, v36
	v_cndmask_b32_e64 v36, v36, -v36, vcc
	v_fmac_f32_e32 v36, v35, v34
	v_mov_b32_e32 v34, v36
.LBB0_799:
	s_or_b64 exec, exec, s[10:11]
	v_or_b32_e32 v48, 32, v89
	v_or_b32_e32 v35, v48, v90
	v_lshl_add_u32 v36, v35, 2, v234
	ds_read_b32 v50, v36
	v_cvt_pk_bf16_f32 v34, v34, s0
	global_store_short v[64:65], v34, off offset:64
	v_add_u32_e32 v34, s2, v35
	v_lshrrev_b32_e32 v36, 6, v34
	s_waitcnt lgkmcnt(0)
	v_mul_f32_e32 v18, v18, v50
	v_cndmask_b32_e64 v51, v35, v36, s[8:9]
	s_and_saveexec_b64 s[10:11], s[12:13]
	s_cbranch_execz .LBB0_801
	v_and_b32_e32 v35, 63, v51
	v_cvt_f32_ubyte0_e32 v35, v35
	v_mul_f32_e32 v35, v86, v35
	v_mul_f32_e32 v35, 0.15915494, v35
	v_mov_b32_dpp v36, v18 row_ror:8 row_mask:0xf bank_mask:0xf
	v_sin_f32_e32 v37, v35
	v_cos_f32_e32 v35, v35
	s_waitcnt lgkmcnt(0)
	v_mul_f32_e32 v36, v37, v36
	v_cndmask_b32_e64 v36, v36, -v36, vcc
	v_fmac_f32_e32 v36, v35, v18
	v_mov_b32_e32 v18, v36
.LBB0_801:
	s_or_b64 exec, exec, s[10:11]
	v_or_b32_e32 v36, v48, v69
	v_lshl_add_u32 v35, v36, 2, v234
	ds_read_b32 v53, v35
	v_cvt_pk_bf16_f32 v18, v18, s0
	v_mad_i64_i32 v[34:35], s[4:5], v34, s44, v[66:67]
	global_store_short v[34:35], v18, off
	v_add_u32_e32 v18, s2, v36
	v_lshrrev_b32_e32 v37, 6, v18
	s_waitcnt lgkmcnt(0)
	v_mul_f32_e32 v19, v19, v53
	v_cndmask_b32_e64 v52, v36, v37, s[8:9]
	s_and_saveexec_b64 s[10:11], s[12:13]
	s_cbranch_execz .LBB0_803
	v_and_b32_e32 v36, 63, v52
	v_cvt_f32_ubyte0_e32 v36, v36
	v_mul_f32_e32 v36, v86, v36
	v_mul_f32_e32 v36, 0.15915494, v36
	v_mov_b32_dpp v37, v19 row_ror:8 row_mask:0xf bank_mask:0xf
	v_sin_f32_e32 v38, v36
	v_cos_f32_e32 v36, v36
	s_waitcnt lgkmcnt(0)
	v_mul_f32_e32 v37, v38, v37
	v_cndmask_b32_e64 v37, v37, -v37, vcc
	v_fmac_f32_e32 v37, v36, v19
	v_mov_b32_e32 v19, v37
.LBB0_803:
	s_or_b64 exec, exec, s[10:11]
	v_or_b32_e32 v37, v48, v88
	v_cvt_pk_bf16_f32 v36, v19, s0
	v_lshl_add_u32 v19, v37, 2, v234
	ds_read_b32 v55, v19
	v_mad_i64_i32 v[18:19], s[4:5], v18, s44, v[66:67]
	global_store_short v[18:19], v36, off
	v_add_u32_e32 v36, s2, v37
	v_lshrrev_b32_e32 v38, 6, v36
	s_waitcnt lgkmcnt(0)
	v_mul_f32_e32 v20, v20, v55
	v_cndmask_b32_e64 v54, v37, v38, s[8:9]
	s_and_saveexec_b64 s[10:11], s[12:13]
	s_cbranch_execz .LBB0_805
	v_and_b32_e32 v37, 63, v54
	v_cvt_f32_ubyte0_e32 v37, v37
	v_mul_f32_e32 v37, v86, v37
	v_mul_f32_e32 v37, 0.15915494, v37
	v_mov_b32_dpp v38, v20 row_ror:8 row_mask:0xf bank_mask:0xf
	v_sin_f32_e32 v39, v37
	v_cos_f32_e32 v37, v37
	s_waitcnt lgkmcnt(0)
	v_mul_f32_e32 v38, v39, v38
	v_cndmask_b32_e64 v38, v38, -v38, vcc
	v_fmac_f32_e32 v38, v37, v20
	v_mov_b32_e32 v20, v38
; DI int crow(int r, int hh) { return (r & 3) + 8 * (r >> 2) + 4 * hh; }
; DI void rope_consts(int e, int t, float& sn, float& cs) {
;   const int i8 = e & 7;
;   const float inv = __builtin_amdgcn_exp2f(-(float)i8 * 1.6609640474436813f);
;   const float pos = (e < 16) ? (float)(t >> 6) : (float)(t & 63);
;   const float rev = pos * inv * 0.15915494309189535f;
;   sn = __builtin_amdgcn_sinf(rev);
;   cs = __builtin_amdgcn_cosf(rev);
; }
; DI void p3_qproj(KP p, int u, char* smem, int l) {
;     ...
; #pragma unroll
;       for (int r = 0; r < 16; ++r) {
;         const int ml = ml0 + crow(r, hh);
;         const int row = mt * 128 + ml;
;         float v = acc[i][j][r] * rs[ml];
;         if (rope) {
;           float sn, cs;
;           rope_consts(l31, row & 4095, sn, cs);
;           float pr = __shfl_xor(v, 8);
;           v = (l31 & 8) ? (v * cs + pr * sn) : (v * cs - pr * sn);
;         }
;         Q[(size_t)row * 768 + n0 + l31] = f2bf(v);
;       }
.LBB0_805:
	s_or_b64 exec, exec, s[10:11]
	v_or_b32_e32 v38, v48, v91
	v_lshl_add_u32 v37, v38, 2, v234
	ds_read_b32 v57, v37
	v_cvt_pk_bf16_f32 v20, v20, s0
	v_mad_i64_i32 v[36:37], s[4:5], v36, s44, v[66:67]
	global_store_short v[36:37], v20, off
	v_add_u32_e32 v20, s2, v38
	v_lshrrev_b32_e32 v39, 6, v20
	s_waitcnt lgkmcnt(0)
	v_mul_f32_e32 v21, v21, v57
	v_cndmask_b32_e64 v56, v38, v39, s[8:9]
	s_and_saveexec_b64 s[10:11], s[12:13]
	s_cbranch_execz .LBB0_807
	v_and_b32_e32 v38, 63, v56
	v_cvt_f32_ubyte0_e32 v38, v38
	v_mul_f32_e32 v38, v86, v38
	v_mul_f32_e32 v38, 0.15915494, v38
	v_mov_b32_dpp v39, v21 row_ror:8 row_mask:0xf bank_mask:0xf
	v_sin_f32_e32 v40, v38
	v_cos_f32_e32 v38, v38
	s_waitcnt lgkmcnt(0)
	v_mul_f32_e32 v39, v40, v39
	v_cndmask_b32_e64 v39, v39, -v39, vcc
	v_fmac_f32_e32 v39, v38, v21
	v_mov_b32_e32 v21, v39
.LBB0_807:
	s_or_b64 exec, exec, s[10:11]
	v_or_b32_e32 v39, v48, v92
	v_cvt_pk_bf16_f32 v38, v21, s0
	v_lshl_add_u32 v21, v39, 2, v234
	ds_read_b32 v59, v21
	v_mad_i64_i32 v[20:21], s[4:5], v20, s44, v[66:67]
	global_store_short v[20:21], v38, off
	v_add_u32_e32 v38, s2, v39
	v_lshrrev_b32_e32 v40, 6, v38
	s_waitcnt lgkmcnt(0)
	v_mul_f32_e32 v22, v22, v59
	v_cndmask_b32_e64 v58, v39, v40, s[8:9]
	s_and_saveexec_b64 s[10:11], s[12:13]
	s_cbranch_execz .LBB0_809
	v_and_b32_e32 v39, 63, v58
	v_cvt_f32_ubyte0_e32 v39, v39
	v_mul_f32_e32 v39, v86, v39
	v_mul_f32_e32 v39, 0.15915494, v39
	v_mov_b32_dpp v40, v22 row_ror:8 row_mask:0xf bank_mask:0xf
	v_sin_f32_e32 v41, v39
	v_cos_f32_e32 v39, v39
	s_waitcnt lgkmcnt(0)
	v_mul_f32_e32 v40, v41, v40
	v_cndmask_b32_e64 v40, v40, -v40, vcc
	v_fmac_f32_e32 v40, v39, v22
	v_mov_b32_e32 v22, v40
.LBB0_809:
	s_or_b64 exec, exec, s[10:11]
	v_or_b32_e32 v40, v48, v93
	v_lshl_add_u32 v39, v40, 2, v234
	ds_read_b32 v61, v39
	v_cvt_pk_bf16_f32 v22, v22, s0
	v_mad_i64_i32 v[38:39], s[4:5], v38, s44, v[66:67]
	global_store_short v[38:39], v22, off
	v_add_u32_e32 v22, s2, v40
	v_lshrrev_b32_e32 v41, 6, v22
	s_waitcnt lgkmcnt(0)
	v_mul_f32_e32 v23, v23, v61
	v_cndmask_b32_e64 v60, v40, v41, s[8:9]
	s_and_saveexec_b64 s[10:11], s[12:13]
	s_cbranch_execz .LBB0_811
	v_and_b32_e32 v40, 63, v60
	v_cvt_f32_ubyte0_e32 v40, v40
	v_mul_f32_e32 v40, v86, v40
	v_mul_f32_e32 v40, 0.15915494, v40
	v_mov_b32_dpp v41, v23 row_ror:8 row_mask:0xf bank_mask:0xf
	v_sin_f32_e32 v42, v40
	v_cos_f32_e32 v40, v40
	s_waitcnt lgkmcnt(0)
	v_mul_f32_e32 v41, v42, v41
	v_cndmask_b32_e64 v41, v41, -v41, vcc
	v_fmac_f32_e32 v41, v40, v23
	v_mov_b32_e32 v23, v41
.LBB0_811:
	s_or_b64 exec, exec, s[10:11]
	v_or_b32_e32 v41, v48, v94
	v_cvt_pk_bf16_f32 v40, v23, s0
	v_lshl_add_u32 v23, v41, 2, v234
	ds_read_b32 v63, v23
	v_mad_i64_i32 v[22:23], s[4:5], v22, s44, v[66:67]
	global_store_short v[22:23], v40, off
	v_add_u32_e32 v40, s2, v41
	v_lshrrev_b32_e32 v42, 6, v40
	s_waitcnt lgkmcnt(0)
	v_mul_f32_e32 v24, v24, v63
	v_cndmask_b32_e64 v62, v41, v42, s[8:9]
	s_and_saveexec_b64 s[10:11], s[12:13]
	s_cbranch_execz .LBB0_813
	v_and_b32_e32 v41, 63, v62
	v_cvt_f32_ubyte0_e32 v41, v41
	v_mul_f32_e32 v41, v86, v41
	v_mul_f32_e32 v41, 0.15915494, v41
	v_mov_b32_dpp v42, v24 row_ror:8 row_mask:0xf bank_mask:0xf
	v_sin_f32_e32 v43, v41
	v_cos_f32_e32 v41, v41
	s_waitcnt lgkmcnt(0)
	v_mul_f32_e32 v42, v43, v42
	v_cndmask_b32_e64 v42, v42, -v42, vcc
	v_fmac_f32_e32 v42, v41, v24
	v_mov_b32_e32 v24, v42
.LBB0_813:
	s_or_b64 exec, exec, s[10:11]
	v_or_b32_e32 v42, v48, v95
	v_lshl_add_u32 v41, v42, 2, v234
	ds_read_b32 v65, v41
	v_cvt_pk_bf16_f32 v24, v24, s0
	v_mad_i64_i32 v[40:41], s[4:5], v40, s44, v[66:67]
	global_store_short v[40:41], v24, off
	v_add_u32_e32 v24, s2, v42
	v_lshrrev_b32_e32 v43, 6, v24
	s_waitcnt lgkmcnt(0)
	v_mul_f32_e32 v25, v25, v65
	v_cndmask_b32_e64 v64, v42, v43, s[8:9]
	s_and_saveexec_b64 s[10:11], s[12:13]
	s_cbranch_execz .LBB0_815
	v_and_b32_e32 v42, 63, v64
	v_cvt_f32_ubyte0_e32 v42, v42
	v_mul_f32_e32 v42, v86, v42
	v_mul_f32_e32 v42, 0.15915494, v42
	v_mov_b32_dpp v43, v25 row_ror:8 row_mask:0xf bank_mask:0xf
	v_sin_f32_e32 v44, v42
	v_cos_f32_e32 v42, v42
	s_waitcnt lgkmcnt(0)
	v_mul_f32_e32 v43, v44, v43
	v_cndmask_b32_e64 v43, v43, -v43, vcc
	v_fmac_f32_e32 v43, v42, v25
	v_mov_b32_e32 v25, v43
.LBB0_815:
	s_or_b64 exec, exec, s[10:11]
	v_or_b32_e32 v43, v48, v96
	v_cvt_pk_bf16_f32 v42, v25, s0
	v_lshl_add_u32 v25, v43, 2, v234
	ds_read_b32 v69, v25
	v_mad_i64_i32 v[24:25], s[4:5], v24, s44, v[66:67]
	global_store_short v[24:25], v42, off
	v_add_u32_e32 v42, s2, v43
	v_lshrrev_b32_e32 v44, 6, v42
	s_waitcnt lgkmcnt(0)
	v_mul_f32_e32 v26, v26, v69
	v_cndmask_b32_e64 v68, v43, v44, s[8:9]
	s_and_saveexec_b64 s[10:11], s[12:13]
	s_cbranch_execz .LBB0_817
	v_and_b32_e32 v43, 63, v68
	v_cvt_f32_ubyte0_e32 v43, v43
	v_mul_f32_e32 v43, v86, v43
	v_mul_f32_e32 v43, 0.15915494, v43
	v_mov_b32_dpp v44, v26 row_ror:8 row_mask:0xf bank_mask:0xf
	v_sin_f32_e32 v45, v43
	v_cos_f32_e32 v43, v43
	s_waitcnt lgkmcnt(0)
	v_mul_f32_e32 v44, v45, v44
	v_cndmask_b32_e64 v44, v44, -v44, vcc
	v_fmac_f32_e32 v44, v43, v26
	v_mov_b32_e32 v26, v44
.LBB0_817:
	s_or_b64 exec, exec, s[10:11]
	v_or_b32_e32 v44, v48, v97
	v_lshl_add_u32 v43, v44, 2, v234
	ds_read_b32 v71, v43
	v_cvt_pk_bf16_f32 v26, v26, s0
	v_mad_i64_i32 v[42:43], s[4:5], v42, s44, v[66:67]
	global_store_short v[42:43], v26, off
	v_add_u32_e32 v26, s2, v44
	v_lshrrev_b32_e32 v45, 6, v26
	s_waitcnt lgkmcnt(0)
	v_mul_f32_e32 v27, v27, v71
	v_cndmask_b32_e64 v70, v44, v45, s[8:9]
	s_and_saveexec_b64 s[10:11], s[12:13]
	s_cbranch_execz .LBB0_819
	v_and_b32_e32 v44, 63, v70
	v_cvt_f32_ubyte0_e32 v44, v44
	v_mul_f32_e32 v44, v86, v44
	v_mul_f32_e32 v44, 0.15915494, v44
	v_mov_b32_dpp v45, v27 row_ror:8 row_mask:0xf bank_mask:0xf
	v_sin_f32_e32 v46, v44
	v_cos_f32_e32 v44, v44
	s_waitcnt lgkmcnt(0)
	v_mul_f32_e32 v45, v46, v45
	v_cndmask_b32_e64 v45, v45, -v45, vcc
	v_fmac_f32_e32 v45, v44, v27
	v_mov_b32_e32 v27, v45
; DI int crow(int r, int hh) { return (r & 3) + 8 * (r >> 2) + 4 * hh; }
; DI void rope_consts(int e, int t, float& sn, float& cs) {
;   const int i8 = e & 7;
;   const float inv = __builtin_amdgcn_exp2f(-(float)i8 * 1.6609640474436813f);
;   const float pos = (e < 16) ? (float)(t >> 6) : (float)(t & 63);
;   const float rev = pos * inv * 0.15915494309189535f;
;   sn = __builtin_amdgcn_sinf(rev);
;   cs = __builtin_amdgcn_cosf(rev);
; }
; DI void p3_qproj(KP p, int u, char* smem, int l) {
;     ...
; #pragma unroll
;       for (int r = 0; r < 16; ++r) {
;         const int ml = ml0 + crow(r, hh);
;         const int row = mt * 128 + ml;
;         float v = acc[i][j][r] * rs[ml];
;         if (rope) {
;           float sn, cs;
;           rope_consts(l31, row & 4095, sn, cs);
;           float pr = __shfl_xor(v, 8);
;           v = (l31 & 8) ? (v * cs + pr * sn) : (v * cs - pr * sn);
;         }
;         Q[(size_t)row * 768 + n0 + l31] = f2bf(v);
;       }
.LBB0_819:
	s_or_b64 exec, exec, s[10:11]
	v_or_b32_e32 v45, v48, v98
	v_cvt_pk_bf16_f32 v44, v27, s0
	v_lshl_add_u32 v27, v45, 2, v234
	ds_read_b32 v73, v27
	v_mad_i64_i32 v[26:27], s[4:5], v26, s44, v[66:67]
	global_store_short v[26:27], v44, off
	v_add_u32_e32 v44, s2, v45
	v_lshrrev_b32_e32 v46, 6, v44
	s_waitcnt lgkmcnt(0)
	v_mul_f32_e32 v28, v28, v73
	v_cndmask_b32_e64 v72, v45, v46, s[8:9]
	s_and_saveexec_b64 s[10:11], s[12:13]
	s_cbranch_execz .LBB0_821
	v_and_b32_e32 v45, 63, v72
	v_cvt_f32_ubyte0_e32 v45, v45
	v_mul_f32_e32 v45, v86, v45
	v_mul_f32_e32 v45, 0.15915494, v45
	v_mov_b32_dpp v46, v28 row_ror:8 row_mask:0xf bank_mask:0xf
	v_sin_f32_e32 v47, v45
	v_cos_f32_e32 v45, v45
	s_waitcnt lgkmcnt(0)
	v_mul_f32_e32 v46, v47, v46
	v_cndmask_b32_e64 v46, v46, -v46, vcc
	v_fmac_f32_e32 v46, v45, v28
	v_mov_b32_e32 v28, v46
.LBB0_821:
	s_or_b64 exec, exec, s[10:11]
	v_or_b32_e32 v46, v48, v99
	v_lshl_add_u32 v45, v46, 2, v234
	ds_read_b32 v75, v45
	v_cvt_pk_bf16_f32 v28, v28, s0
	v_mad_i64_i32 v[44:45], s[4:5], v44, s44, v[66:67]
	global_store_short v[44:45], v28, off
	v_add_u32_e32 v28, s2, v46
	v_lshrrev_b32_e32 v47, 6, v28
	s_waitcnt lgkmcnt(0)
	v_mul_f32_e32 v29, v29, v75
	v_cndmask_b32_e64 v74, v46, v47, s[8:9]
	s_and_saveexec_b64 s[10:11], s[12:13]
	s_cbranch_execz .LBB0_823
	v_and_b32_e32 v46, 63, v74
	v_cvt_f32_ubyte0_e32 v46, v46
	v_mul_f32_e32 v46, v86, v46
	v_mul_f32_e32 v46, 0.15915494, v46
	v_mov_b32_dpp v47, v29 row_ror:8 row_mask:0xf bank_mask:0xf
	v_sin_f32_e32 v49, v46
	v_cos_f32_e32 v46, v46
	s_waitcnt lgkmcnt(0)
	v_mul_f32_e32 v47, v49, v47
	v_cndmask_b32_e64 v47, v47, -v47, vcc
	v_fmac_f32_e32 v47, v46, v29
	v_mov_b32_e32 v29, v47
.LBB0_823:
	s_or_b64 exec, exec, s[10:11]
	v_or_b32_e32 v47, v48, v100
	v_cvt_pk_bf16_f32 v46, v29, s0
	v_lshl_add_u32 v29, v47, 2, v234
	ds_read_b32 v77, v29
	v_mad_i64_i32 v[28:29], s[4:5], v28, s44, v[66:67]
	global_store_short v[28:29], v46, off
	v_add_u32_e32 v46, s2, v47
	v_lshrrev_b32_e32 v49, 6, v46
	s_waitcnt lgkmcnt(0)
	v_mul_f32_e32 v30, v30, v77
	v_cndmask_b32_e64 v76, v47, v49, s[8:9]
	s_and_saveexec_b64 s[10:11], s[12:13]
	s_cbranch_execz .LBB0_825
	v_and_b32_e32 v47, 63, v76
	v_cvt_f32_ubyte0_e32 v47, v47
	v_mul_f32_e32 v47, v86, v47
	v_mul_f32_e32 v47, 0.15915494, v47
	v_mov_b32_dpp v49, v30 row_ror:8 row_mask:0xf bank_mask:0xf
	v_sin_f32_e32 v78, v47
	v_cos_f32_e32 v47, v47
	s_waitcnt lgkmcnt(0)
	v_mul_f32_e32 v49, v78, v49
	v_cndmask_b32_e64 v49, v49, -v49, vcc
	v_fmac_f32_e32 v49, v47, v30
	v_mov_b32_e32 v30, v49
.LBB0_825:
	s_or_b64 exec, exec, s[10:11]
	v_or_b32_e32 v49, v48, v101
	v_lshl_add_u32 v47, v49, 2, v234
	ds_read_b32 v79, v47
	v_cvt_pk_bf16_f32 v30, v30, s0
	v_mad_i64_i32 v[46:47], s[4:5], v46, s44, v[66:67]
	global_store_short v[46:47], v30, off
	v_add_u32_e32 v30, s2, v49
	v_lshrrev_b32_e32 v78, 6, v30
	s_waitcnt lgkmcnt(0)
	v_mul_f32_e32 v31, v31, v79
	v_cndmask_b32_e64 v78, v49, v78, s[8:9]
	s_and_saveexec_b64 s[10:11], s[12:13]
	s_cbranch_execz .LBB0_827
	v_and_b32_e32 v49, 63, v78
	v_cvt_f32_ubyte0_e32 v49, v49
	v_mul_f32_e32 v49, v86, v49
	v_mul_f32_e32 v49, 0.15915494, v49
	v_mov_b32_dpp v80, v31 row_ror:8 row_mask:0xf bank_mask:0xf
	v_sin_f32_e32 v81, v49
	v_cos_f32_e32 v49, v49
	s_waitcnt lgkmcnt(0)
	v_mul_f32_e32 v80, v81, v80
	v_cndmask_b32_e64 v80, v80, -v80, vcc
	v_fmac_f32_e32 v80, v49, v31
	v_mov_b32_e32 v31, v80
.LBB0_827:
	s_or_b64 exec, exec, s[10:11]
	v_or_b32_e32 v80, v48, v102
	v_cvt_pk_bf16_f32 v49, v31, s0
	v_lshl_add_u32 v31, v80, 2, v234
	ds_read_b32 v81, v31
	v_mad_i64_i32 v[30:31], s[4:5], v30, s44, v[66:67]
	global_store_short v[30:31], v49, off
	v_add_u32_e32 v49, s2, v80
	v_lshrrev_b32_e32 v82, 6, v49
	s_waitcnt lgkmcnt(0)
	v_mul_f32_e32 v32, v32, v81
	v_cndmask_b32_e64 v80, v80, v82, s[8:9]
	s_and_saveexec_b64 s[10:11], s[12:13]
	s_cbranch_execz .LBB0_829
	v_and_b32_e32 v82, 63, v80
	v_cvt_f32_ubyte0_e32 v82, v82
	v_mul_f32_e32 v82, v86, v82
	v_mul_f32_e32 v82, 0.15915494, v82
	v_mov_b32_dpp v83, v32 row_ror:8 row_mask:0xf bank_mask:0xf
	v_sin_f32_e32 v84, v82
	v_cos_f32_e32 v82, v82
	s_waitcnt lgkmcnt(0)
	v_mul_f32_e32 v83, v84, v83
	v_cndmask_b32_e64 v83, v83, -v83, vcc
	v_fmac_f32_e32 v83, v82, v32
	v_mov_b32_e32 v32, v83
.LBB0_829:
	s_or_b64 exec, exec, s[10:11]
	v_or_b32_e32 v82, v48, v103
	v_lshl_add_u32 v48, v82, 2, v234
	ds_read_b32 v83, v48
	v_cvt_pk_bf16_f32 v32, v32, s0
	v_mad_i64_i32 v[48:49], s[4:5], v49, s44, v[66:67]
	global_store_short v[48:49], v32, off
	v_add_u32_e32 v32, s2, v82
	v_lshrrev_b32_e32 v84, 6, v32
	s_waitcnt lgkmcnt(0)
	v_mul_f32_e32 v33, v33, v83
	v_cndmask_b32_e64 v82, v82, v84, s[8:9]
	s_and_saveexec_b64 s[8:9], s[12:13]
	s_cbranch_execz .LBB0_831
	v_and_b32_e32 v84, 63, v82
	v_cvt_f32_ubyte0_e32 v84, v84
	v_mul_f32_e32 v84, v86, v84
	v_mul_f32_e32 v84, 0.15915494, v84
	v_mov_b32_dpp v85, v33 row_ror:8 row_mask:0xf bank_mask:0xf
	v_sin_f32_e32 v88, v84
	v_cos_f32_e32 v84, v84
	s_waitcnt lgkmcnt(0)
	v_mul_f32_e32 v85, v88, v85
	v_cndmask_b32_e64 v85, v85, -v85, vcc
	v_fmac_f32_e32 v85, v84, v33
	v_mov_b32_e32 v33, v85
.LBB0_831:
	s_or_b64 exec, exec, s[8:9]
	v_cvt_pk_bf16_f32 v84, v33, s0
	v_mad_i64_i32 v[32:33], s[2:3], v32, s44, v[66:67]
	v_mul_f32_e32 v2, v2, v50
	global_store_short v[32:33], v84, off
	s_and_saveexec_b64 s[8:9], s[6:7]
	s_cbranch_execz .LBB0_833
	v_and_b32_e32 v50, 63, v51
	v_cvt_f32_ubyte0_e32 v50, v50
	v_mul_f32_e32 v50, v86, v50
	v_mul_f32_e32 v50, 0.15915494, v50
	v_mov_b32_dpp v51, v2 row_ror:8 row_mask:0xf bank_mask:0xf
	v_sin_f32_e32 v66, v50
	v_cos_f32_e32 v50, v50
	s_waitcnt lgkmcnt(0)
	v_mul_f32_e32 v51, v66, v51
	v_cndmask_b32_e64 v51, v51, -v51, vcc
	v_fmac_f32_e32 v51, v50, v2
	v_mov_b32_e32 v2, v51
; DI int crow(int r, int hh) { return (r & 3) + 8 * (r >> 2) + 4 * hh; }
; DI void rope_consts(int e, int t, float& sn, float& cs) {
;   const int i8 = e & 7;
;   const float inv = __builtin_amdgcn_exp2f(-(float)i8 * 1.6609640474436813f);
;   const float pos = (e < 16) ? (float)(t >> 6) : (float)(t & 63);
;   const float rev = pos * inv * 0.15915494309189535f;
;   sn = __builtin_amdgcn_sinf(rev);
;   cs = __builtin_amdgcn_cosf(rev);
; }
; DI void p3_qproj(KP p, int u, char* smem, int l) {
;     ...
; #pragma unroll
;       for (int r = 0; r < 16; ++r) {
;         const int ml = ml0 + crow(r, hh);
;         const int row = mt * 128 + ml;
;         float v = acc[i][j][r] * rs[ml];
;         if (rope) {
;           float sn, cs;
;           rope_consts(l31, row & 4095, sn, cs);
;           float pr = __shfl_xor(v, 8);
;           v = (l31 & 8) ? (v * cs + pr * sn) : (v * cs - pr * sn);
;         }
;         Q[(size_t)row * 768 + n0 + l31] = f2bf(v);
;       }
.LBB0_833:
	s_or_b64 exec, exec, s[8:9]
	v_cvt_pk_bf16_f32 v2, v2, s0
	global_store_short v[34:35], v2, off offset:64
	v_mul_f32_e32 v2, v3, v53
	s_and_saveexec_b64 s[8:9], s[6:7]
	s_cbranch_execz .LBB0_835
	v_and_b32_e32 v3, 63, v52
	v_cvt_f32_ubyte0_e32 v3, v3
	v_mul_f32_e32 v3, v86, v3
	v_mul_f32_e32 v3, 0.15915494, v3
	v_mov_b32_dpp v34, v2 row_ror:8 row_mask:0xf bank_mask:0xf
	v_sin_f32_e32 v35, v3
	v_cos_f32_e32 v3, v3
	s_waitcnt lgkmcnt(0)
	v_mul_f32_e32 v34, v35, v34
	v_cndmask_b32_e64 v34, v34, -v34, vcc
	v_fmac_f32_e32 v34, v3, v2
	v_mov_b32_e32 v2, v34
.LBB0_835:
	s_or_b64 exec, exec, s[8:9]
	v_cvt_pk_bf16_f32 v2, v2, s0
	global_store_short v[18:19], v2, off offset:64
	v_mul_f32_e32 v2, v4, v55
	s_and_saveexec_b64 s[8:9], s[6:7]
	s_cbranch_execz .LBB0_837
	v_and_b32_e32 v3, 63, v54
	v_cvt_f32_ubyte0_e32 v3, v3
	v_mul_f32_e32 v3, v86, v3
	v_mul_f32_e32 v3, 0.15915494, v3
	v_mov_b32_dpp v4, v2 row_ror:8 row_mask:0xf bank_mask:0xf
	v_sin_f32_e32 v18, v3
	v_cos_f32_e32 v3, v3
	s_waitcnt lgkmcnt(0)
	v_mul_f32_e32 v4, v18, v4
	v_cndmask_b32_e64 v4, v4, -v4, vcc
	v_fmac_f32_e32 v4, v3, v2
	v_mov_b32_e32 v2, v4
.LBB0_837:
	s_or_b64 exec, exec, s[8:9]
	v_cvt_pk_bf16_f32 v2, v2, s0
	global_store_short v[36:37], v2, off offset:64
	v_mul_f32_e32 v2, v5, v57
	s_and_saveexec_b64 s[8:9], s[6:7]
	s_cbranch_execz .LBB0_839
	v_and_b32_e32 v3, 63, v56
	v_cvt_f32_ubyte0_e32 v3, v3
	v_mul_f32_e32 v3, v86, v3
	v_mul_f32_e32 v3, 0.15915494, v3
	v_mov_b32_dpp v4, v2 row_ror:8 row_mask:0xf bank_mask:0xf
	v_sin_f32_e32 v5, v3
	v_cos_f32_e32 v3, v3
	s_waitcnt lgkmcnt(0)
	v_mul_f32_e32 v4, v5, v4
	v_cndmask_b32_e64 v4, v4, -v4, vcc
	v_fmac_f32_e32 v4, v3, v2
	v_mov_b32_e32 v2, v4
.LBB0_839:
	s_or_b64 exec, exec, s[8:9]
	v_cvt_pk_bf16_f32 v2, v2, s0
	global_store_short v[20:21], v2, off offset:64
	v_mul_f32_e32 v2, v6, v59
	s_and_saveexec_b64 s[8:9], s[6:7]
	s_cbranch_execz .LBB0_841
	v_and_b32_e32 v3, 63, v58
	v_cvt_f32_ubyte0_e32 v3, v3
	v_mul_f32_e32 v3, v86, v3
	v_mul_f32_e32 v3, 0.15915494, v3
	v_mov_b32_dpp v4, v2 row_ror:8 row_mask:0xf bank_mask:0xf
	v_sin_f32_e32 v5, v3
	v_cos_f32_e32 v3, v3
	s_waitcnt lgkmcnt(0)
	v_mul_f32_e32 v4, v5, v4
	v_cndmask_b32_e64 v4, v4, -v4, vcc
	v_fmac_f32_e32 v4, v3, v2
	v_mov_b32_e32 v2, v4
.LBB0_841:
	s_or_b64 exec, exec, s[8:9]
	v_cvt_pk_bf16_f32 v2, v2, s0
	global_store_short v[38:39], v2, off offset:64
	v_mul_f32_e32 v2, v7, v61
	s_and_saveexec_b64 s[8:9], s[6:7]
	s_cbranch_execz .LBB0_843
	v_and_b32_e32 v3, 63, v60
	v_cvt_f32_ubyte0_e32 v3, v3
	v_mul_f32_e32 v3, v86, v3
	v_mul_f32_e32 v3, 0.15915494, v3
	v_mov_b32_dpp v4, v2 row_ror:8 row_mask:0xf bank_mask:0xf
	v_sin_f32_e32 v5, v3
	v_cos_f32_e32 v3, v3
	s_waitcnt lgkmcnt(0)
	v_mul_f32_e32 v4, v5, v4
	v_cndmask_b32_e64 v4, v4, -v4, vcc
	v_fmac_f32_e32 v4, v3, v2
	v_mov_b32_e32 v2, v4
.LBB0_843:
	s_or_b64 exec, exec, s[8:9]
	v_cvt_pk_bf16_f32 v2, v2, s0
	global_store_short v[22:23], v2, off offset:64
	v_mul_f32_e32 v2, v8, v63
	s_and_saveexec_b64 s[8:9], s[6:7]
	s_cbranch_execz .LBB0_845
	v_and_b32_e32 v3, 63, v62
	v_cvt_f32_ubyte0_e32 v3, v3
	v_mul_f32_e32 v3, v86, v3
	v_mul_f32_e32 v3, 0.15915494, v3
	v_mov_b32_dpp v4, v2 row_ror:8 row_mask:0xf bank_mask:0xf
	v_sin_f32_e32 v5, v3
	v_cos_f32_e32 v3, v3
	s_waitcnt lgkmcnt(0)
	v_mul_f32_e32 v4, v5, v4
	v_cndmask_b32_e64 v4, v4, -v4, vcc
	v_fmac_f32_e32 v4, v3, v2
	v_mov_b32_e32 v2, v4
.LBB0_845:
	s_or_b64 exec, exec, s[8:9]
	v_cvt_pk_bf16_f32 v2, v2, s0
	global_store_short v[40:41], v2, off offset:64
	v_mul_f32_e32 v2, v9, v65
	s_and_saveexec_b64 s[8:9], s[6:7]
	s_cbranch_execz .LBB0_847
	v_and_b32_e32 v3, 63, v64
	v_cvt_f32_ubyte0_e32 v3, v3
	v_mul_f32_e32 v3, v86, v3
	v_mul_f32_e32 v3, 0.15915494, v3
	v_mov_b32_dpp v4, v2 row_ror:8 row_mask:0xf bank_mask:0xf
	v_sin_f32_e32 v5, v3
	v_cos_f32_e32 v3, v3
	s_waitcnt lgkmcnt(0)
	v_mul_f32_e32 v4, v5, v4
	v_cndmask_b32_e64 v4, v4, -v4, vcc
	v_fmac_f32_e32 v4, v3, v2
	v_mov_b32_e32 v2, v4
.LBB0_847:
	s_or_b64 exec, exec, s[8:9]
	v_cvt_pk_bf16_f32 v2, v2, s0
	global_store_short v[24:25], v2, off offset:64
	v_mul_f32_e32 v2, v10, v69
	s_and_saveexec_b64 s[8:9], s[6:7]
	s_cbranch_execz .LBB0_849
	v_and_b32_e32 v3, 63, v68
	v_cvt_f32_ubyte0_e32 v3, v3
	v_mul_f32_e32 v3, v86, v3
	v_mul_f32_e32 v3, 0.15915494, v3
	v_mov_b32_dpp v4, v2 row_ror:8 row_mask:0xf bank_mask:0xf
	v_sin_f32_e32 v5, v3
	v_cos_f32_e32 v3, v3
	s_waitcnt lgkmcnt(0)
	v_mul_f32_e32 v4, v5, v4
	v_cndmask_b32_e64 v4, v4, -v4, vcc
	v_fmac_f32_e32 v4, v3, v2
	v_mov_b32_e32 v2, v4
; DI int crow(int r, int hh) { return (r & 3) + 8 * (r >> 2) + 4 * hh; }
; DI void rope_consts(int e, int t, float& sn, float& cs) {
;   const int i8 = e & 7;
;   const float inv = __builtin_amdgcn_exp2f(-(float)i8 * 1.6609640474436813f);
;   const float pos = (e < 16) ? (float)(t >> 6) : (float)(t & 63);
;   const float rev = pos * inv * 0.15915494309189535f;
;   sn = __builtin_amdgcn_sinf(rev);
;   cs = __builtin_amdgcn_cosf(rev);
; }
; DI void p3_qproj(KP p, int u, char* smem, int l) {
;     ...
; #pragma unroll
;       for (int r = 0; r < 16; ++r) {
;         const int ml = ml0 + crow(r, hh);
;         const int row = mt * 128 + ml;
;         float v = acc[i][j][r] * rs[ml];
;         if (rope) {
;           float sn, cs;
;           rope_consts(l31, row & 4095, sn, cs);
;           float pr = __shfl_xor(v, 8);
;           v = (l31 & 8) ? (v * cs + pr * sn) : (v * cs - pr * sn);
;         }
;         Q[(size_t)row * 768 + n0 + l31] = f2bf(v);
;       }
.LBB0_849:
	s_or_b64 exec, exec, s[8:9]
	v_cvt_pk_bf16_f32 v2, v2, s0
	global_store_short v[42:43], v2, off offset:64
	v_mul_f32_e32 v2, v11, v71
	s_and_saveexec_b64 s[8:9], s[6:7]
	s_cbranch_execz .LBB0_851
	v_and_b32_e32 v3, 63, v70
	v_cvt_f32_ubyte0_e32 v3, v3
	v_mul_f32_e32 v3, v86, v3
	v_mul_f32_e32 v3, 0.15915494, v3
	v_mov_b32_dpp v4, v2 row_ror:8 row_mask:0xf bank_mask:0xf
	v_sin_f32_e32 v5, v3
	v_cos_f32_e32 v3, v3
	s_waitcnt lgkmcnt(0)
	v_mul_f32_e32 v4, v5, v4
	v_cndmask_b32_e64 v4, v4, -v4, vcc
	v_fmac_f32_e32 v4, v3, v2
	v_mov_b32_e32 v2, v4
.LBB0_851:
	s_or_b64 exec, exec, s[8:9]
	v_cvt_pk_bf16_f32 v2, v2, s0
	global_store_short v[26:27], v2, off offset:64
	v_mul_f32_e32 v2, v12, v73
	s_and_saveexec_b64 s[8:9], s[6:7]
	s_cbranch_execz .LBB0_853
	v_and_b32_e32 v3, 63, v72
	v_cvt_f32_ubyte0_e32 v3, v3
	v_mul_f32_e32 v3, v86, v3
	v_mul_f32_e32 v3, 0.15915494, v3
	v_mov_b32_dpp v4, v2 row_ror:8 row_mask:0xf bank_mask:0xf
	v_sin_f32_e32 v5, v3
	v_cos_f32_e32 v3, v3
	s_waitcnt lgkmcnt(0)
	v_mul_f32_e32 v4, v5, v4
	v_cndmask_b32_e64 v4, v4, -v4, vcc
	v_fmac_f32_e32 v4, v3, v2
	v_mov_b32_e32 v2, v4
.LBB0_853:
	s_or_b64 exec, exec, s[8:9]
	v_cvt_pk_bf16_f32 v2, v2, s0
	global_store_short v[44:45], v2, off offset:64
	v_mul_f32_e32 v2, v13, v75
	s_and_saveexec_b64 s[8:9], s[6:7]
	s_cbranch_execz .LBB0_855
	v_and_b32_e32 v3, 63, v74
	v_cvt_f32_ubyte0_e32 v3, v3
	v_mul_f32_e32 v3, v86, v3
	v_mul_f32_e32 v3, 0.15915494, v3
	v_mov_b32_dpp v4, v2 row_ror:8 row_mask:0xf bank_mask:0xf
	v_sin_f32_e32 v5, v3
	v_cos_f32_e32 v3, v3
	s_waitcnt lgkmcnt(0)
	v_mul_f32_e32 v4, v5, v4
	v_cndmask_b32_e64 v4, v4, -v4, vcc
	v_fmac_f32_e32 v4, v3, v2
	v_mov_b32_e32 v2, v4
.LBB0_855:
	s_or_b64 exec, exec, s[8:9]
	v_cvt_pk_bf16_f32 v2, v2, s0
	global_store_short v[28:29], v2, off offset:64
	v_mul_f32_e32 v2, v14, v77
	s_and_saveexec_b64 s[8:9], s[6:7]
	s_cbranch_execz .LBB0_857
	v_and_b32_e32 v3, 63, v76
	v_cvt_f32_ubyte0_e32 v3, v3
	v_mul_f32_e32 v3, v86, v3
	v_mul_f32_e32 v3, 0.15915494, v3
	v_mov_b32_dpp v4, v2 row_ror:8 row_mask:0xf bank_mask:0xf
	v_sin_f32_e32 v5, v3
	v_cos_f32_e32 v3, v3
	s_waitcnt lgkmcnt(0)
	v_mul_f32_e32 v4, v5, v4
	v_cndmask_b32_e64 v4, v4, -v4, vcc
	v_fmac_f32_e32 v4, v3, v2
	v_mov_b32_e32 v2, v4
.LBB0_857:
	s_or_b64 exec, exec, s[8:9]
	v_cvt_pk_bf16_f32 v2, v2, s0
	global_store_short v[46:47], v2, off offset:64
	v_mul_f32_e32 v2, v15, v79
	s_and_saveexec_b64 s[8:9], s[6:7]
	s_cbranch_execz .LBB0_859
	v_and_b32_e32 v3, 63, v78
	v_cvt_f32_ubyte0_e32 v3, v3
	v_mul_f32_e32 v3, v86, v3
	v_mul_f32_e32 v3, 0.15915494, v3
	v_mov_b32_dpp v4, v2 row_ror:8 row_mask:0xf bank_mask:0xf
	v_sin_f32_e32 v5, v3
	v_cos_f32_e32 v3, v3
	s_waitcnt lgkmcnt(0)
	v_mul_f32_e32 v4, v5, v4
	v_cndmask_b32_e64 v4, v4, -v4, vcc
	v_fmac_f32_e32 v4, v3, v2
	v_mov_b32_e32 v2, v4
.LBB0_859:
	s_or_b64 exec, exec, s[8:9]
	v_cvt_pk_bf16_f32 v2, v2, s0
	global_store_short v[30:31], v2, off offset:64
	v_mul_f32_e32 v2, v16, v81
	s_and_saveexec_b64 s[8:9], s[6:7]
	s_cbranch_execz .LBB0_861
	v_and_b32_e32 v3, 63, v80
	v_cvt_f32_ubyte0_e32 v3, v3
	v_mul_f32_e32 v3, v86, v3
	v_mul_f32_e32 v3, 0.15915494, v3
	v_mov_b32_dpp v4, v2 row_ror:8 row_mask:0xf bank_mask:0xf
	v_sin_f32_e32 v5, v3
	v_cos_f32_e32 v3, v3
	s_waitcnt lgkmcnt(0)
	v_mul_f32_e32 v4, v5, v4
	v_cndmask_b32_e64 v4, v4, -v4, vcc
	v_fmac_f32_e32 v4, v3, v2
	v_mov_b32_e32 v2, v4
.LBB0_861:
	s_or_b64 exec, exec, s[8:9]
	v_cvt_pk_bf16_f32 v2, v2, s0
	global_store_short v[48:49], v2, off offset:64
	v_mul_f32_e32 v2, v17, v83
	s_and_saveexec_b64 s[8:9], s[6:7]
	s_cbranch_execz .LBB0_514
	v_and_b32_e32 v3, 63, v82
	v_cvt_f32_ubyte0_e32 v3, v3
	v_mul_f32_e32 v3, v86, v3
	v_mul_f32_e32 v3, 0.15915494, v3
	v_mov_b32_dpp v4, v2 row_ror:8 row_mask:0xf bank_mask:0xf
	v_sin_f32_e32 v5, v3
	v_cos_f32_e32 v3, v3
	s_waitcnt lgkmcnt(0)
	v_mul_f32_e32 v4, v5, v4
	v_cndmask_b32_e64 v4, v4, -v4, vcc
	v_fmac_f32_e32 v4, v3, v2
	v_mov_b32_e32 v2, v4
	s_branch .LBB0_514
